# RG-LRU first unit: conv taps/bias staged with one load per thread issued before the weight-image loads (was: generic strided loops with their own exposed round trip)
# baseline (speedup 1.0000x reference)
.LBB0_245:
	v_mov_b32_e32 v90, v177
	s_andn2_b64 vcc, exec, s[4:5]
	v_readfirstlane_b32 s20, v90
	s_waitcnt vmcnt(4)
	v_lshlrev_b32_e32 v8, 4, v90
	s_barrier
	s_cbranch_vccnz .LBB0_264
	s_waitcnt vmcnt(0)
	v_mul_f32_e32 v149, 0xbfb8aa3b, v149
	v_exp_f32_e32 v149, v149
	s_nop 0
	v_add_f32_e32 v152, 1.0, v149
	v_add_f32_e32 v153, -1.0, v152
	v_frexp_mant_f32_e32 v154, v152
	v_cvt_f64_f32_e32 v[16:17], v152
	v_sub_f32_e32 v155, v153, v152
	v_frexp_exp_i32_f64_e32 v16, v[16:17]
	v_cmp_gt_f32_e32 vcc, s88, v154
	v_sub_f32_e32 v153, v149, v153
	v_add_f32_e32 v150, 1.0, v155
	v_subbrev_co_u32_e32 v16, vcc, 0, v16, vcc
	v_add_f32_e32 v150, v153, v150
	v_sub_u32_e32 v153, 0, v16
	v_cvt_f32_i32_e32 v16, v16
	v_ldexp_f32 v152, v152, v153
	v_ldexp_f32 v150, v150, v153
	v_add_f32_e32 v153, -1.0, v152
	v_add_f32_e32 v154, 1.0, v152
	v_add_f32_e32 v155, 1.0, v153
	v_add_f32_e32 v156, -1.0, v154
	v_sub_f32_e32 v155, v152, v155
	v_sub_f32_e32 v152, v152, v156
	v_mul_f32_e32 v156, 0x3f317218, v16
	v_add_f32_e32 v155, v150, v155
	v_add_f32_e32 v150, v150, v152
	v_fma_f32 v152, v16, s89, -v156
	v_add_f32_e32 v157, v153, v155
	v_add_f32_e32 v158, v154, v150
	v_fmac_f32_e32 v152, 0xb102e308, v16
	v_sub_f32_e32 v16, v157, v153
	v_sub_f32_e32 v153, v158, v154
	v_rcp_f32_e32 v154, v158
	v_add_f32_e32 v159, v156, v152
	v_sub_f32_e32 v150, v150, v153
	v_sub_f32_e32 v153, v159, v156
	v_sub_f32_e32 v152, v152, v153
	v_mul_f32_e32 v153, v157, v154
	v_sub_f32_e32 v16, v155, v16
	v_mul_f32_e32 v155, v158, v153
	v_fma_f32 v156, v153, v158, -v155
	v_fmac_f32_e32 v156, v153, v150
	v_add_f32_e32 v160, v155, v156
	v_sub_f32_e32 v161, v157, v160
	v_sub_f32_e32 v155, v160, v155
	v_sub_f32_e32 v157, v157, v161
	v_sub_f32_e32 v155, v155, v156
	v_sub_f32_e32 v156, v157, v160
	v_add_f32_e32 v16, v16, v156
	v_add_f32_e32 v16, v155, v16
	v_add_f32_e32 v155, v161, v16
	v_mul_f32_e32 v156, v154, v155
	v_sub_f32_e32 v157, v161, v155
	v_mul_f32_e32 v160, v158, v156
	v_add_f32_e32 v16, v16, v157
	v_add_f32_e32 v157, v153, v156
	v_fma_f32 v158, v156, v158, -v160
	v_sub_f32_e32 v153, v157, v153
	v_fmac_f32_e32 v158, v156, v150
	v_sub_f32_e32 v150, v156, v153
	v_add_f32_e32 v153, v160, v158
	v_sub_f32_e32 v156, v153, v160
	v_sub_f32_e32 v160, v155, v153
	v_sub_f32_e32 v155, v155, v160
	v_sub_f32_e32 v153, v155, v153
	v_sub_f32_e32 v156, v156, v158
	v_add_f32_e32 v16, v16, v153
	v_add_f32_e32 v16, v156, v16
	v_add_f32_e32 v16, v160, v16
	v_mul_f32_e32 v16, v154, v16
	v_add_f32_e32 v16, v150, v16
	v_add_f32_e32 v150, v157, v16
	v_mul_f32_e32 v153, v150, v150
	v_fmamk_f32 v156, v153, 0x3e9b6dac, v127
	v_sub_f32_e32 v154, v150, v157
	v_ldexp_f32 v155, v150, 1
	v_mul_f32_e32 v150, v150, v153
	v_fmaak_f32 v153, v153, v156, 0x3f2aaada
	v_mul_f32_e32 v150, v150, v153
	v_add_f32_e32 v153, v155, v150
	v_sub_f32_e32 v16, v16, v154
	v_sub_f32_e32 v154, v153, v155
	v_ldexp_f32 v16, v16, 1
	v_sub_f32_e32 v150, v150, v154
	v_add_f32_e32 v16, v16, v150
	v_add_f32_e32 v150, v153, v16
	v_sub_f32_e32 v153, v150, v153
	v_add_f32_e32 v154, v159, v150
	v_sub_f32_e32 v16, v16, v153
	v_sub_f32_e32 v153, v154, v159
	v_sub_f32_e32 v155, v154, v153
	v_sub_f32_e32 v150, v150, v153
	v_add_f32_e32 v153, v152, v16
	v_sub_f32_e32 v155, v159, v155
	v_sub_f32_e32 v156, v153, v152
	v_add_f32_e32 v150, v150, v155
	v_sub_f32_e32 v155, v153, v156
	v_sub_f32_e32 v16, v16, v156
	v_sub_f32_e32 v152, v152, v155
	v_add_f32_e32 v150, v153, v150
	v_add_f32_e32 v16, v16, v152
	v_add_f32_e32 v152, v154, v150
	v_sub_f32_e32 v153, v152, v154
	v_sub_f32_e32 v150, v150, v153
	v_add_f32_e32 v16, v16, v150
	v_add_f32_e32 v16, v152, v16
	v_cmp_neq_f32_e32 vcc, s90, v149
	v_cndmask_b32_e32 v16, v130, v16, vcc
	v_cmp_ngt_f32_e32 vcc, -1.0, v149
	v_cndmask_b32_e32 v16, v131, v16, vcc
	v_cmp_neq_f32_e32 vcc, -1.0, v149
	v_cndmask_b32_e32 v16, v132, v16, vcc
	v_cmp_lt_f32_e64 vcc, |v149|, s91
	v_cndmask_b32_e32 v16, v16, v149, vcc
	v_mul_f32_e32 v149, 0xc1000000, v16
	ds_write_b32 v136, v149
	v_and_b32_e32 v238, 0x7f, v177
	v_lshrrev_b32_e32 v239, 7, v177
	v_or_b32_e32 v238, s73, v238
	v_lshl_or_b32 v238, v239, 10, v238
	v_lshlrev_b32_e32 v238, 2, v238
	global_load_dword v240, v238, s[26:27]
	v_or_b32_e32 v239, s73, v177
	v_lshlrev_b32_e32 v239, 2, v239
	v_cmp_gt_u32_e32 vcc, 0x80, v177
	s_and_saveexec_b64 s[100:101], vcc
	global_load_dword v241, v239, s[28:29]
	s_mov_b64 exec, s[100:101]
	v_add_u32_e32 v91, 0x200, v90
	v_add_u32_e32 v10, 0x400, v90
	v_add_u32_e32 v12, 0x600, v90
	v_add_u32_e32 v18, 0x800, v90
	v_add_u32_e32 v20, 0xa00, v90
	v_add_u32_e32 v28, 0xc00, v90
	v_add_u32_e32 v30, 0xe00, v90
	v_ashrrev_i32_e32 v9, 4, v90
	s_waitcnt vmcnt(3)
	v_ashrrev_i32_e32 v34, 4, v91
	v_ashrrev_i32_e32 v35, 4, v10
	v_ashrrev_i32_e32 v36, 4, v12
	v_ashrrev_i32_e32 v37, 4, v18
	v_ashrrev_i32_e32 v38, 4, v20
	v_ashrrev_i32_e32 v39, 4, v28
	v_ashrrev_i32_e32 v40, 4, v30
	v_and_b32_e32 v88, 0xf0, v8
	v_lshlrev_b32_e32 v0, 7, v9
	v_lshlrev_b32_e32 v2, 7, v34
	v_lshlrev_b32_e32 v10, 7, v35
	v_lshlrev_b32_e32 v12, 7, v36
	v_lshlrev_b32_e32 v18, 7, v37
	v_lshlrev_b32_e32 v20, 7, v38
	v_lshlrev_b32_e32 v28, 7, v39
	v_lshlrev_b32_e32 v30, 7, v40
	v_lshl_add_u64 v[26:27], s[22:23], 0, v[88:89]
	v_ashrrev_i32_e32 v1, 31, v0
	v_ashrrev_i32_e32 v3, 31, v2
	v_ashrrev_i32_e32 v11, 31, v10
	v_ashrrev_i32_e32 v13, 31, v12
	v_ashrrev_i32_e32 v19, 31, v18
	v_ashrrev_i32_e32 v21, 31, v20
	v_ashrrev_i32_e32 v29, 31, v28
	v_ashrrev_i32_e32 v31, 31, v30
	v_lshl_add_u64 v[0:1], v[0:1], 1, v[26:27]
	v_lshl_add_u64 v[4:5], v[2:3], 1, v[26:27]
	v_lshl_add_u64 v[10:11], v[10:11], 1, v[26:27]
	v_lshl_add_u64 v[14:15], v[12:13], 1, v[26:27]
	v_lshl_add_u64 v[18:19], v[18:19], 1, v[26:27]
	v_lshl_add_u64 v[22:23], v[20:21], 1, v[26:27]
	v_lshl_add_u64 v[28:29], v[28:29], 1, v[26:27]
	v_lshl_add_u64 v[30:31], v[30:31], 1, v[26:27]
	global_load_dwordx4 v[0:3], v[0:1], off
	s_nop 0
	global_load_dwordx4 v[4:7], v[4:5], off
	s_nop 0
	global_load_dwordx4 v[10:13], v[10:11], off
	s_nop 0
	global_load_dwordx4 v[14:17], v[14:15], off
	s_nop 0
	global_load_dwordx4 v[18:21], v[18:19], off
	s_nop 0
	global_load_dwordx4 v[22:25], v[22:23], off
	s_nop 0
	global_load_dwordx4 v[26:29], v[28:29], off
	s_nop 0
	global_load_dwordx4 v[30:33], v[30:31], off
	v_and_b32_e32 v41, 0x70, v90
	v_xad_u32 v41, v88, v41, 16
	v_lshl_add_u32 v9, v9, 8, v41
	v_cmp_gt_i32_e32 vcc, s79, v90
	v_lshl_add_u32 v34, v34, 8, v41
	v_lshl_add_u32 v35, v35, 8, v41
	v_lshl_add_u32 v36, v36, 8, v41
	v_lshl_add_u32 v37, v37, 8, v41
	v_lshl_add_u32 v38, v38, 8, v41
	v_lshl_add_u32 v39, v39, 8, v41
	v_lshl_add_u32 v40, v40, 8, v41
	s_waitcnt vmcnt(7)
	ds_write_b128 v9, v[0:3] offset:16384
	s_waitcnt vmcnt(6)
	ds_write_b128 v34, v[4:7] offset:16384
	s_waitcnt vmcnt(5)
	ds_write_b128 v35, v[10:13] offset:16384
	s_waitcnt vmcnt(4)
	ds_write_b128 v36, v[14:17] offset:16384
	s_waitcnt vmcnt(3)
	ds_write_b128 v37, v[18:21] offset:16384
	s_waitcnt vmcnt(2)
	ds_write_b128 v38, v[22:25] offset:16384
	s_waitcnt vmcnt(1)
	ds_write_b128 v39, v[26:29] offset:16384
	s_waitcnt vmcnt(0)
	ds_write_b128 v40, v[30:33] offset:16384
	v_lshl_add_u32 v238, v177, 2, s82
	ds_write_b32 v238, v240
	v_cmp_gt_u32_e32 vcc, 0x80, v177
	s_and_saveexec_b64 s[100:101], vcc
	ds_write_b32 v238, v241 offset:2048
	s_mov_b64 exec, s[100:101]
.LBB0_263:
.LBB0_264:
	s_and_b32 s65, s96, 63
	s_ashr_i32 s64, s20, 6
	s_lshl_b32 s4, s65, 8
	s_lshl_b32 s5, s64, 5
	v_and_b32_e32 v93, 31, v90
	s_add_i32 s12, s5, s4
	v_or_b32_e32 v9, s12, v93
	v_add_u32_e32 v0, -2, v9
	v_cmp_gt_u32_e32 vcc, s84, v0
	v_bfe_u32 v92, v90, 5, 1
	s_lshl_b32 s20, s73, 1
	v_cndmask_b32_e32 v2, v9, v0, vcc
	v_mov_b64_e32 v[0:1], s[52:53]
	v_mad_i64_i32 v[2:3], s[4:5], v2, s85, v[0:1]
	v_lshl_add_u64 v[2:3], v[2:3], 0, s[20:21]
	v_lshlrev_b32_e32 v88, 4, v92
	v_lshl_add_u64 v[4:5], v[2:3], 0, v[88:89]
	v_add_co_u32_e64 v2, s[4:5], s86, v4
	s_waitcnt lgkmcnt(0)
	s_nop 0
	v_addc_co_u32_e64 v3, s[4:5], 0, v5, s[4:5]
	s_barrier
	global_load_dwordx4 v[10:13], v[2:3], off offset:1024
	global_load_dwordx4 v[178:181], v[2:3], off offset:1056
	global_load_dwordx4 v[194:197], v[2:3], off offset:1088
	global_load_dwordx4 v[210:213], v[2:3], off offset:1120
	global_load_dwordx4 v[226:229], v[2:3], off offset:1152
	global_load_dwordx4 v[242:245], v[2:3], off offset:1184
	v_add_u32_e32 v2, -1, v9
	v_cmp_gt_u32_e64 s[4:5], s84, v2
	v_add_u32_e32 v18, 1, v9
	s_cmpk_lt_u32 s12, 0x4000
	v_cndmask_b32_e64 v2, v9, v2, s[4:5]
	v_mad_i64_i32 v[2:3], s[6:7], v2, s85, v[0:1]
	v_lshl_add_u64 v[2:3], v[2:3], 0, s[20:21]
	v_lshl_add_u64 v[2:3], v[2:3], 0, v[88:89]
	v_add_co_u32_e64 v6, s[6:7], s86, v2
	v_lshlrev_b32_e32 v91, 8, v93
	s_nop 0
	v_addc_co_u32_e64 v7, s[6:7], 0, v3, s[6:7]
	global_load_dwordx4 v[14:17], v[6:7], off offset:1024
	global_load_dwordx4 v[182:185], v[6:7], off offset:1056
	global_load_dwordx4 v[198:201], v[6:7], off offset:1088
	global_load_dwordx4 v[214:217], v[6:7], off offset:1120
	global_load_dwordx4 v[230:233], v[6:7], off offset:1152
	global_load_dwordx4 v[246:249], v[6:7], off offset:1184
	v_mad_i64_i32 v[6:7], s[6:7], v9, s85, v[0:1]
	v_cmp_gt_u32_e64 s[6:7], s84, v18
	v_lshl_add_u64 v[6:7], v[6:7], 0, s[20:21]
	v_lshl_add_u64 v[52:53], v[6:7], 0, v[88:89]
	v_cndmask_b32_e64 v9, v9, v18, s[6:7]
	v_mad_i64_i32 v[0:1], s[8:9], v9, s85, v[0:1]
	v_add_co_u32_e64 v6, s[8:9], s86, v52
	v_lshl_add_u64 v[0:1], v[0:1], 0, s[20:21]
	s_nop 0
	v_addc_co_u32_e64 v7, s[8:9], 0, v53, s[8:9]
	global_load_dwordx4 v[18:21], v[6:7], off offset:1024
	global_load_dwordx4 v[186:189], v[6:7], off offset:1056
	global_load_dwordx4 v[202:205], v[6:7], off offset:1088
	global_load_dwordx4 v[218:221], v[6:7], off offset:1120
	global_load_dwordx4 v[234:237], v[6:7], off offset:1152
	global_load_dwordx4 v[252:255], v[6:7], off offset:1184
	v_lshl_add_u64 v[6:7], v[0:1], 0, v[88:89]
	v_add_co_u32_e64 v0, s[8:9], s86, v6
	v_lshl_add_u32 v9, v92, 5, 16
	s_nop 0
	v_addc_co_u32_e64 v1, s[8:9], 0, v7, s[8:9]
	global_load_dwordx4 v[22:25], v[0:1], off offset:1024
	global_load_dwordx4 v[190:193], v[0:1], off offset:1056
	global_load_dwordx4 v[206:209], v[0:1], off offset:1088
	global_load_dwordx4 v[222:225], v[0:1], off offset:1120
	global_load_dwordx4 v[238:241], v[0:1], off offset:1152
	global_load_dwordx4 v[168:171], v[0:1], off offset:1184
	s_waitcnt vmcnt(26)
	s_waitcnt lgkmcnt(4)
	v_lshl_add_u64 v[0:1], v[4:5], 0, s[38:39]
	s_cselect_b64 s[8:9], -1, 0
	v_lshl_add_u64 v[6:7], v[6:7], 0, s[38:39]
	v_or_b32_e32 v138, s73, v93
	v_and_b32_e32 v8, 0x70, v8
	v_add_u32_e32 v94, 16, v91
	s_waitcnt vmcnt(23)
	s_waitcnt vmcnt(17)
	s_waitcnt lgkmcnt(3)
	s_waitcnt lgkmcnt(1)
	s_waitcnt lgkmcnt(0)
	s_waitcnt vmcnt(11)
	s_waitcnt vmcnt(5)
	ds_read_b128 v[26:29], v9 offset:10240
	ds_read_b128 v[30:33], v9 offset:10256
	ds_read_b128 v[34:37], v9 offset:8192
	ds_read_b128 v[38:41], v9 offset:8208
	ds_read_b128 v[42:45], v9 offset:8704
	ds_read_b128 v[80:83], v9 offset:8720
	s_mov_b64 exec, vcc
	v_lshlrev_b32_e32 v4, 16, v10
	v_and_b32_e32 v5, 0xffff0000, v10
	v_lshlrev_b32_e32 v46, 16, v11
	v_and_b32_e32 v47, 0xffff0000, v11
	s_waitcnt lgkmcnt(2)
	v_pk_fma_f32 v[26:27], v[34:35], v[4:5], v[26:27]
	v_pk_fma_f32 v[28:29], v[36:37], v[46:47], v[28:29]
	v_lshlrev_b32_e32 v84, 16, v12
	v_and_b32_e32 v85, 0xffff0000, v12
	v_lshlrev_b32_e32 v86, 16, v13
	v_and_b32_e32 v87, 0xffff0000, v13
	v_pk_fma_f32 v[30:31], v[38:39], v[84:85], v[30:31]
	v_pk_fma_f32 v[32:33], v[40:41], v[86:87], v[32:33]
	s_mov_b64 exec, -1
	ds_read_b128 v[34:37], v9 offset:9216
	ds_read_b128 v[38:41], v9 offset:9232
	s_mov_b64 exec, s[4:5]
	v_lshlrev_b32_e32 v4, 16, v14
	v_and_b32_e32 v5, 0xffff0000, v14
	v_lshlrev_b32_e32 v46, 16, v15
	v_and_b32_e32 v47, 0xffff0000, v15
	s_waitcnt lgkmcnt(2)
	v_pk_fma_f32 v[26:27], v[42:43], v[4:5], v[26:27]
	v_pk_fma_f32 v[28:29], v[44:45], v[46:47], v[28:29]
	v_lshlrev_b32_e32 v84, 16, v16
	v_and_b32_e32 v85, 0xffff0000, v16
	v_lshlrev_b32_e32 v86, 16, v17
	v_and_b32_e32 v87, 0xffff0000, v17
	v_pk_fma_f32 v[30:31], v[80:81], v[84:85], v[30:31]
	v_pk_fma_f32 v[32:33], v[82:83], v[86:87], v[32:33]
	s_mov_b64 exec, -1
	ds_read_b128 v[42:45], v9 offset:9728
	ds_read_b128 v[80:83], v9 offset:9744
	v_lshlrev_b32_e32 v4, 16, v18
	v_and_b32_e32 v5, 0xffff0000, v18
	v_lshlrev_b32_e32 v46, 16, v19
	v_and_b32_e32 v47, 0xffff0000, v19
	s_waitcnt lgkmcnt(2)
	v_pk_fma_f32 v[26:27], v[34:35], v[4:5], v[26:27]
	v_pk_fma_f32 v[28:29], v[36:37], v[46:47], v[28:29]
	v_lshlrev_b32_e32 v84, 16, v20
	v_and_b32_e32 v85, 0xffff0000, v20
	v_lshlrev_b32_e32 v86, 16, v21
	v_and_b32_e32 v87, 0xffff0000, v21
	v_pk_fma_f32 v[30:31], v[38:39], v[84:85], v[30:31]
	v_pk_fma_f32 v[32:33], v[40:41], v[86:87], v[32:33]
	s_mov_b64 exec, s[6:7]
	v_lshlrev_b32_e32 v4, 16, v22
	v_and_b32_e32 v5, 0xffff0000, v22
	v_lshlrev_b32_e32 v46, 16, v23
	v_and_b32_e32 v47, 0xffff0000, v23
	s_waitcnt lgkmcnt(0)
	v_pk_fma_f32 v[26:27], v[42:43], v[4:5], v[26:27]
	v_pk_fma_f32 v[28:29], v[44:45], v[46:47], v[28:29]
	v_lshlrev_b32_e32 v84, 16, v24
	v_and_b32_e32 v85, 0xffff0000, v24
	v_lshlrev_b32_e32 v86, 16, v25
	v_and_b32_e32 v87, 0xffff0000, v25
	v_pk_fma_f32 v[30:31], v[80:81], v[84:85], v[30:31]
	v_pk_fma_f32 v[32:33], v[82:83], v[86:87], v[32:33]
	s_mov_b64 exec, -1
	v_cvt_pk_bf16_f32 v48, v26, v27
	v_cvt_pk_bf16_f32 v49, v28, v29
	v_cvt_pk_bf16_f32 v50, v30, v31
	v_cvt_pk_bf16_f32 v51, v32, v33
	s_waitcnt lgkmcnt(3)
	s_waitcnt lgkmcnt(1)
	s_waitcnt lgkmcnt(0)
	s_nop 0
	v_lshl_add_u64 v[4:5], v[2:3], 0, s[38:39]
	v_lshl_add_u64 v[2:3], v[52:53], 0, s[38:39]
	s_waitcnt vmcnt(4)
	s_waitcnt vmcnt(4)
	s_waitcnt lgkmcnt(3)
	s_waitcnt lgkmcnt(1)
	s_waitcnt lgkmcnt(0)
	s_waitcnt vmcnt(4)
	ds_read_b128 v[26:29], v9 offset:10304
	ds_read_b128 v[30:33], v9 offset:10320
	ds_read_b128 v[34:37], v9 offset:8256
	ds_read_b128 v[38:41], v9 offset:8272
	ds_read_b128 v[42:45], v9 offset:8768
	ds_read_b128 v[80:83], v9 offset:8784
	s_mov_b64 exec, vcc
	v_lshlrev_b32_e32 v46, 16, v178
	v_and_b32_e32 v47, 0xffff0000, v178
	v_lshlrev_b32_e32 v84, 16, v179
	v_and_b32_e32 v85, 0xffff0000, v179
	s_waitcnt lgkmcnt(2)
	v_pk_fma_f32 v[26:27], v[34:35], v[46:47], v[26:27]
	v_pk_fma_f32 v[28:29], v[36:37], v[84:85], v[28:29]
	v_lshlrev_b32_e32 v86, 16, v180
	v_and_b32_e32 v87, 0xffff0000, v180
	v_lshlrev_b32_e32 v96, 16, v181
	v_and_b32_e32 v97, 0xffff0000, v181
	v_pk_fma_f32 v[30:31], v[38:39], v[86:87], v[30:31]
	v_pk_fma_f32 v[32:33], v[40:41], v[96:97], v[32:33]
	s_mov_b64 exec, -1
	ds_read_b128 v[34:37], v9 offset:9280
	ds_read_b128 v[38:41], v9 offset:9296
	s_mov_b64 exec, s[4:5]
	v_lshlrev_b32_e32 v46, 16, v182
	v_and_b32_e32 v47, 0xffff0000, v182
	v_lshlrev_b32_e32 v84, 16, v183
	v_and_b32_e32 v85, 0xffff0000, v183
	s_waitcnt lgkmcnt(2)
	v_pk_fma_f32 v[26:27], v[42:43], v[46:47], v[26:27]
	v_pk_fma_f32 v[28:29], v[44:45], v[84:85], v[28:29]
	v_lshlrev_b32_e32 v86, 16, v184
	v_and_b32_e32 v87, 0xffff0000, v184
	v_lshlrev_b32_e32 v96, 16, v185
	v_and_b32_e32 v97, 0xffff0000, v185
	v_pk_fma_f32 v[30:31], v[80:81], v[86:87], v[30:31]
	v_pk_fma_f32 v[32:33], v[82:83], v[96:97], v[32:33]
	s_mov_b64 exec, -1
	ds_read_b128 v[42:45], v9 offset:9792
	ds_read_b128 v[80:83], v9 offset:9808
	v_lshlrev_b32_e32 v46, 16, v186
	v_and_b32_e32 v47, 0xffff0000, v186
	v_lshlrev_b32_e32 v84, 16, v187
	v_and_b32_e32 v85, 0xffff0000, v187
	s_waitcnt lgkmcnt(2)
	v_pk_fma_f32 v[26:27], v[34:35], v[46:47], v[26:27]
	v_pk_fma_f32 v[28:29], v[36:37], v[84:85], v[28:29]
	v_lshlrev_b32_e32 v86, 16, v188
	v_and_b32_e32 v87, 0xffff0000, v188
	v_lshlrev_b32_e32 v96, 16, v189
	v_and_b32_e32 v97, 0xffff0000, v189
	v_pk_fma_f32 v[30:31], v[38:39], v[86:87], v[30:31]
	v_pk_fma_f32 v[32:33], v[40:41], v[96:97], v[32:33]
	s_mov_b64 exec, s[6:7]
	v_lshlrev_b32_e32 v46, 16, v190
	v_and_b32_e32 v47, 0xffff0000, v190
	v_lshlrev_b32_e32 v84, 16, v191
	v_and_b32_e32 v85, 0xffff0000, v191
	s_waitcnt lgkmcnt(0)
	v_pk_fma_f32 v[26:27], v[42:43], v[46:47], v[26:27]
	v_pk_fma_f32 v[28:29], v[44:45], v[84:85], v[28:29]
	v_lshlrev_b32_e32 v86, 16, v192
	v_and_b32_e32 v87, 0xffff0000, v192
	v_lshlrev_b32_e32 v96, 16, v193
	v_and_b32_e32 v97, 0xffff0000, v193
	v_pk_fma_f32 v[30:31], v[80:81], v[86:87], v[30:31]
	v_pk_fma_f32 v[32:33], v[82:83], v[96:97], v[32:33]
	s_mov_b64 exec, -1
	v_cvt_pk_bf16_f32 v52, v26, v27
	v_cvt_pk_bf16_f32 v53, v28, v29
	v_cvt_pk_bf16_f32 v54, v30, v31
	v_cvt_pk_bf16_f32 v55, v32, v33
	s_waitcnt lgkmcnt(3)
	s_waitcnt lgkmcnt(1)
	s_waitcnt lgkmcnt(0)
	s_nop 0
	global_load_dwordx4 v[178:181], v[0:1], off offset:192
	global_load_dwordx4 v[182:185], v[4:5], off offset:192
	global_load_dwordx4 v[186:189], v[2:3], off offset:192
	global_load_dwordx4 v[190:193], v[6:7], off offset:192
	s_waitcnt vmcnt(7)
	s_waitcnt vmcnt(7)
	s_waitcnt lgkmcnt(3)
	s_waitcnt lgkmcnt(1)
	s_waitcnt lgkmcnt(0)
	s_waitcnt vmcnt(7)
	s_waitcnt vmcnt(7)
	ds_read_b128 v[26:29], v9 offset:10368
	ds_read_b128 v[30:33], v9 offset:10384
	ds_read_b128 v[34:37], v9 offset:8320
	ds_read_b128 v[38:41], v9 offset:8336
	ds_read_b128 v[42:45], v9 offset:8832
	ds_read_b128 v[80:83], v9 offset:8848
	s_mov_b64 exec, vcc
	v_lshlrev_b32_e32 v46, 16, v194
	v_and_b32_e32 v47, 0xffff0000, v194
	v_lshlrev_b32_e32 v84, 16, v195
	v_and_b32_e32 v85, 0xffff0000, v195
	s_waitcnt lgkmcnt(2)
	v_pk_fma_f32 v[26:27], v[34:35], v[46:47], v[26:27]
	v_pk_fma_f32 v[28:29], v[36:37], v[84:85], v[28:29]
	v_lshlrev_b32_e32 v86, 16, v196
	v_and_b32_e32 v87, 0xffff0000, v196
	v_lshlrev_b32_e32 v96, 16, v197
	v_and_b32_e32 v97, 0xffff0000, v197
	v_pk_fma_f32 v[30:31], v[38:39], v[86:87], v[30:31]
	v_pk_fma_f32 v[32:33], v[40:41], v[96:97], v[32:33]
	s_mov_b64 exec, -1
	ds_read_b128 v[34:37], v9 offset:9344
	ds_read_b128 v[38:41], v9 offset:9360
	s_mov_b64 exec, s[4:5]
	v_lshlrev_b32_e32 v46, 16, v198
	v_and_b32_e32 v47, 0xffff0000, v198
	v_lshlrev_b32_e32 v84, 16, v199
	v_and_b32_e32 v85, 0xffff0000, v199
	s_waitcnt lgkmcnt(2)
	v_pk_fma_f32 v[26:27], v[42:43], v[46:47], v[26:27]
	v_pk_fma_f32 v[28:29], v[44:45], v[84:85], v[28:29]
	v_lshlrev_b32_e32 v86, 16, v200
	v_and_b32_e32 v87, 0xffff0000, v200
	v_lshlrev_b32_e32 v96, 16, v201
	v_and_b32_e32 v97, 0xffff0000, v201
	v_pk_fma_f32 v[30:31], v[80:81], v[86:87], v[30:31]
	v_pk_fma_f32 v[32:33], v[82:83], v[96:97], v[32:33]
	s_mov_b64 exec, -1
	ds_read_b128 v[42:45], v9 offset:9856
	ds_read_b128 v[80:83], v9 offset:9872
	v_lshlrev_b32_e32 v46, 16, v202
	v_and_b32_e32 v47, 0xffff0000, v202
	v_lshlrev_b32_e32 v84, 16, v203
	v_and_b32_e32 v85, 0xffff0000, v203
	s_waitcnt lgkmcnt(2)
	v_pk_fma_f32 v[26:27], v[34:35], v[46:47], v[26:27]
	v_pk_fma_f32 v[28:29], v[36:37], v[84:85], v[28:29]
	v_lshlrev_b32_e32 v86, 16, v204
	v_and_b32_e32 v87, 0xffff0000, v204
	v_lshlrev_b32_e32 v96, 16, v205
	v_and_b32_e32 v97, 0xffff0000, v205
	v_pk_fma_f32 v[30:31], v[38:39], v[86:87], v[30:31]
	v_pk_fma_f32 v[32:33], v[40:41], v[96:97], v[32:33]
	s_mov_b64 exec, s[6:7]
	v_lshlrev_b32_e32 v46, 16, v206
	v_and_b32_e32 v47, 0xffff0000, v206
	v_lshlrev_b32_e32 v84, 16, v207
	v_and_b32_e32 v85, 0xffff0000, v207
	s_waitcnt lgkmcnt(0)
	v_pk_fma_f32 v[26:27], v[42:43], v[46:47], v[26:27]
	v_pk_fma_f32 v[28:29], v[44:45], v[84:85], v[28:29]
	v_lshlrev_b32_e32 v86, 16, v208
	v_and_b32_e32 v87, 0xffff0000, v208
	v_lshlrev_b32_e32 v96, 16, v209
	v_and_b32_e32 v97, 0xffff0000, v209
	v_pk_fma_f32 v[30:31], v[80:81], v[86:87], v[30:31]
	v_pk_fma_f32 v[32:33], v[82:83], v[96:97], v[32:33]
	s_mov_b64 exec, -1
	v_cvt_pk_bf16_f32 v56, v26, v27
	v_cvt_pk_bf16_f32 v57, v28, v29
	v_cvt_pk_bf16_f32 v58, v30, v31
	v_cvt_pk_bf16_f32 v59, v32, v33
	s_waitcnt lgkmcnt(3)
	s_waitcnt lgkmcnt(1)
	s_waitcnt lgkmcnt(0)
	s_nop 0
	global_load_dwordx4 v[194:197], v[0:1], off offset:224
	global_load_dwordx4 v[198:201], v[4:5], off offset:224
	global_load_dwordx4 v[202:205], v[2:3], off offset:224
	global_load_dwordx4 v[206:209], v[6:7], off offset:224
	s_waitcnt vmcnt(10)
	s_waitcnt vmcnt(10)
	s_waitcnt lgkmcnt(3)
	s_waitcnt lgkmcnt(1)
	s_waitcnt lgkmcnt(0)
	s_waitcnt vmcnt(10)
	s_waitcnt vmcnt(10)
	ds_read_b128 v[0:3], v9 offset:10432
	ds_read_b128 v[4:7], v9 offset:10448
	ds_read_b128 v[26:29], v9 offset:8384
	ds_read_b128 v[30:33], v9 offset:8400
	ds_read_b128 v[34:37], v9 offset:8896
	ds_read_b128 v[38:41], v9 offset:8912
	s_mov_b64 exec, vcc
	v_lshlrev_b32_e32 v42, 16, v210
	v_and_b32_e32 v43, 0xffff0000, v210
	v_lshlrev_b32_e32 v44, 16, v211
	v_and_b32_e32 v45, 0xffff0000, v211
	s_waitcnt lgkmcnt(2)
	v_pk_fma_f32 v[0:1], v[26:27], v[42:43], v[0:1]
	v_pk_fma_f32 v[2:3], v[28:29], v[44:45], v[2:3]
	v_lshlrev_b32_e32 v46, 16, v212
	v_and_b32_e32 v47, 0xffff0000, v212
	v_lshlrev_b32_e32 v80, 16, v213
	v_and_b32_e32 v81, 0xffff0000, v213
	v_pk_fma_f32 v[4:5], v[30:31], v[46:47], v[4:5]
	v_pk_fma_f32 v[6:7], v[32:33], v[80:81], v[6:7]
	s_mov_b64 exec, -1
	ds_read_b128 v[26:29], v9 offset:9408
	ds_read_b128 v[30:33], v9 offset:9424
	s_mov_b64 exec, s[4:5]
	v_lshlrev_b32_e32 v42, 16, v214
	v_and_b32_e32 v43, 0xffff0000, v214
	v_lshlrev_b32_e32 v44, 16, v215
	v_and_b32_e32 v45, 0xffff0000, v215
	s_waitcnt lgkmcnt(2)
	v_pk_fma_f32 v[0:1], v[34:35], v[42:43], v[0:1]
	v_pk_fma_f32 v[2:3], v[36:37], v[44:45], v[2:3]
	v_lshlrev_b32_e32 v46, 16, v216
	v_and_b32_e32 v47, 0xffff0000, v216
	v_lshlrev_b32_e32 v80, 16, v217
	v_and_b32_e32 v81, 0xffff0000, v217
	v_pk_fma_f32 v[4:5], v[38:39], v[46:47], v[4:5]
	v_pk_fma_f32 v[6:7], v[40:41], v[80:81], v[6:7]
	s_mov_b64 exec, -1
	ds_read_b128 v[34:37], v9 offset:9920
	ds_read_b128 v[38:41], v9 offset:9936
	v_lshlrev_b32_e32 v42, 16, v218
	v_and_b32_e32 v43, 0xffff0000, v218
	v_lshlrev_b32_e32 v44, 16, v219
	v_and_b32_e32 v45, 0xffff0000, v219
	s_waitcnt lgkmcnt(2)
	v_pk_fma_f32 v[0:1], v[26:27], v[42:43], v[0:1]
	v_pk_fma_f32 v[2:3], v[28:29], v[44:45], v[2:3]
	v_lshlrev_b32_e32 v46, 16, v220
	v_and_b32_e32 v47, 0xffff0000, v220
	v_lshlrev_b32_e32 v80, 16, v221
	v_and_b32_e32 v81, 0xffff0000, v221
	v_pk_fma_f32 v[4:5], v[30:31], v[46:47], v[4:5]
	v_pk_fma_f32 v[6:7], v[32:33], v[80:81], v[6:7]
	s_mov_b64 exec, s[6:7]
	v_lshlrev_b32_e32 v42, 16, v222
	v_and_b32_e32 v43, 0xffff0000, v222
	v_lshlrev_b32_e32 v44, 16, v223
	v_and_b32_e32 v45, 0xffff0000, v223
	s_waitcnt lgkmcnt(0)
	v_pk_fma_f32 v[0:1], v[34:35], v[42:43], v[0:1]
	v_pk_fma_f32 v[2:3], v[36:37], v[44:45], v[2:3]
	v_lshlrev_b32_e32 v46, 16, v224
	v_and_b32_e32 v47, 0xffff0000, v224
	v_lshlrev_b32_e32 v80, 16, v225
	v_and_b32_e32 v81, 0xffff0000, v225
	v_pk_fma_f32 v[4:5], v[38:39], v[46:47], v[4:5]
	v_pk_fma_f32 v[6:7], v[40:41], v[80:81], v[6:7]
	s_mov_b64 exec, -1
	v_cvt_pk_bf16_f32 v60, v0, v1
	v_cvt_pk_bf16_f32 v61, v2, v3
	v_cvt_pk_bf16_f32 v62, v4, v5
	v_cvt_pk_bf16_f32 v63, v6, v7
	s_waitcnt lgkmcnt(3)
	s_waitcnt lgkmcnt(1)
	s_waitcnt lgkmcnt(0)
	s_nop 0
	s_waitcnt vmcnt(9)
	s_waitcnt vmcnt(9)
	s_waitcnt lgkmcnt(3)
	s_waitcnt lgkmcnt(1)
	s_waitcnt lgkmcnt(0)
	s_waitcnt vmcnt(9)
	s_waitcnt vmcnt(9)
	ds_read_b128 v[0:3], v9 offset:10496
	ds_read_b128 v[4:7], v9 offset:10512
	ds_read_b128 v[26:29], v9 offset:8448
	ds_read_b128 v[30:33], v9 offset:8464
	ds_read_b128 v[34:37], v9 offset:8960
	ds_read_b128 v[38:41], v9 offset:8976
	s_mov_b64 exec, vcc
	v_lshlrev_b32_e32 v42, 16, v226
	v_and_b32_e32 v43, 0xffff0000, v226
	v_lshlrev_b32_e32 v44, 16, v227
	v_and_b32_e32 v45, 0xffff0000, v227
	s_waitcnt lgkmcnt(2)
	v_pk_fma_f32 v[0:1], v[26:27], v[42:43], v[0:1]
	v_pk_fma_f32 v[2:3], v[28:29], v[44:45], v[2:3]
	v_lshlrev_b32_e32 v46, 16, v228
	v_and_b32_e32 v47, 0xffff0000, v228
	v_lshlrev_b32_e32 v80, 16, v229
	v_and_b32_e32 v81, 0xffff0000, v229
	v_pk_fma_f32 v[4:5], v[30:31], v[46:47], v[4:5]
	v_pk_fma_f32 v[6:7], v[32:33], v[80:81], v[6:7]
	s_mov_b64 exec, -1
	ds_read_b128 v[26:29], v9 offset:9472
	ds_read_b128 v[30:33], v9 offset:9488
	s_mov_b64 exec, s[4:5]
	v_lshlrev_b32_e32 v42, 16, v230
	v_and_b32_e32 v43, 0xffff0000, v230
	v_lshlrev_b32_e32 v44, 16, v231
	v_and_b32_e32 v45, 0xffff0000, v231
	s_waitcnt lgkmcnt(2)
	v_pk_fma_f32 v[0:1], v[34:35], v[42:43], v[0:1]
	v_pk_fma_f32 v[2:3], v[36:37], v[44:45], v[2:3]
	v_lshlrev_b32_e32 v46, 16, v232
	v_and_b32_e32 v47, 0xffff0000, v232
	v_lshlrev_b32_e32 v80, 16, v233
	v_and_b32_e32 v81, 0xffff0000, v233
	v_pk_fma_f32 v[4:5], v[38:39], v[46:47], v[4:5]
	v_pk_fma_f32 v[6:7], v[40:41], v[80:81], v[6:7]
	s_mov_b64 exec, -1
	ds_read_b128 v[34:37], v9 offset:9984
	ds_read_b128 v[38:41], v9 offset:10000
	v_lshlrev_b32_e32 v42, 16, v234
	v_and_b32_e32 v43, 0xffff0000, v234
	v_lshlrev_b32_e32 v44, 16, v235
	v_and_b32_e32 v45, 0xffff0000, v235
	s_waitcnt lgkmcnt(2)
	v_pk_fma_f32 v[0:1], v[26:27], v[42:43], v[0:1]
	v_pk_fma_f32 v[2:3], v[28:29], v[44:45], v[2:3]
	v_lshlrev_b32_e32 v46, 16, v236
	v_and_b32_e32 v47, 0xffff0000, v236
	v_lshlrev_b32_e32 v80, 16, v237
	v_and_b32_e32 v81, 0xffff0000, v237
	v_pk_fma_f32 v[4:5], v[30:31], v[46:47], v[4:5]
	v_pk_fma_f32 v[6:7], v[32:33], v[80:81], v[6:7]
	s_mov_b64 exec, s[6:7]
	v_lshlrev_b32_e32 v42, 16, v238
	v_and_b32_e32 v43, 0xffff0000, v238
	v_lshlrev_b32_e32 v44, 16, v239
	v_and_b32_e32 v45, 0xffff0000, v239
	s_waitcnt lgkmcnt(0)
	v_pk_fma_f32 v[0:1], v[34:35], v[42:43], v[0:1]
	v_pk_fma_f32 v[2:3], v[36:37], v[44:45], v[2:3]
	v_lshlrev_b32_e32 v46, 16, v240
	v_and_b32_e32 v47, 0xffff0000, v240
	v_lshlrev_b32_e32 v80, 16, v241
	v_and_b32_e32 v81, 0xffff0000, v241
	v_pk_fma_f32 v[4:5], v[38:39], v[46:47], v[4:5]
	v_pk_fma_f32 v[6:7], v[40:41], v[80:81], v[6:7]
	s_mov_b64 exec, -1
	v_cvt_pk_bf16_f32 v64, v0, v1
	v_cvt_pk_bf16_f32 v65, v2, v3
	v_cvt_pk_bf16_f32 v66, v4, v5
	v_cvt_pk_bf16_f32 v67, v6, v7
	s_waitcnt lgkmcnt(3)
	s_waitcnt lgkmcnt(1)
	s_waitcnt lgkmcnt(0)
	s_nop 0
	s_waitcnt vmcnt(8)
	s_waitcnt vmcnt(8)
	s_waitcnt lgkmcnt(3)
	s_waitcnt lgkmcnt(1)
	s_waitcnt lgkmcnt(0)
	s_waitcnt vmcnt(8)
	s_waitcnt vmcnt(8)
	ds_read_b128 v[0:3], v9 offset:10560
	ds_read_b128 v[4:7], v9 offset:10576
	ds_read_b128 v[26:29], v9 offset:8512
	ds_read_b128 v[30:33], v9 offset:8528
	ds_read_b128 v[34:37], v9 offset:9024
	ds_read_b128 v[38:41], v9 offset:9040
	s_mov_b64 exec, vcc
	v_lshlrev_b32_e32 v42, 16, v242
	v_and_b32_e32 v43, 0xffff0000, v242
	v_lshlrev_b32_e32 v44, 16, v243
	v_and_b32_e32 v45, 0xffff0000, v243
	s_waitcnt lgkmcnt(2)
	v_pk_fma_f32 v[0:1], v[26:27], v[42:43], v[0:1]
	v_pk_fma_f32 v[2:3], v[28:29], v[44:45], v[2:3]
	v_lshlrev_b32_e32 v46, 16, v244
	v_and_b32_e32 v47, 0xffff0000, v244
	v_lshlrev_b32_e32 v80, 16, v245
	v_and_b32_e32 v81, 0xffff0000, v245
	v_pk_fma_f32 v[4:5], v[30:31], v[46:47], v[4:5]
	v_pk_fma_f32 v[6:7], v[32:33], v[80:81], v[6:7]
	s_mov_b64 exec, -1
	ds_read_b128 v[26:29], v9 offset:9536
	ds_read_b128 v[30:33], v9 offset:9552
	s_mov_b64 exec, s[4:5]
	v_lshlrev_b32_e32 v42, 16, v246
	v_and_b32_e32 v43, 0xffff0000, v246
	v_lshlrev_b32_e32 v44, 16, v247
	v_and_b32_e32 v45, 0xffff0000, v247
	s_waitcnt lgkmcnt(2)
	v_pk_fma_f32 v[0:1], v[34:35], v[42:43], v[0:1]
	v_pk_fma_f32 v[2:3], v[36:37], v[44:45], v[2:3]
	v_lshlrev_b32_e32 v46, 16, v248
	v_and_b32_e32 v47, 0xffff0000, v248
	v_lshlrev_b32_e32 v80, 16, v249
	v_and_b32_e32 v81, 0xffff0000, v249
	v_pk_fma_f32 v[4:5], v[38:39], v[46:47], v[4:5]
	v_pk_fma_f32 v[6:7], v[40:41], v[80:81], v[6:7]
	s_mov_b64 exec, -1
	ds_read_b128 v[34:37], v9 offset:10048
	ds_read_b128 v[38:41], v9 offset:10064
	v_lshlrev_b32_e32 v42, 16, v252
	v_and_b32_e32 v43, 0xffff0000, v252
	v_lshlrev_b32_e32 v44, 16, v253
	v_and_b32_e32 v45, 0xffff0000, v253
	s_waitcnt lgkmcnt(2)
	v_pk_fma_f32 v[0:1], v[26:27], v[42:43], v[0:1]
	v_pk_fma_f32 v[2:3], v[28:29], v[44:45], v[2:3]
	v_lshlrev_b32_e32 v46, 16, v254
	v_and_b32_e32 v47, 0xffff0000, v254
	v_lshlrev_b32_e32 v80, 16, v255
	v_and_b32_e32 v81, 0xffff0000, v255
	v_pk_fma_f32 v[4:5], v[30:31], v[46:47], v[4:5]
	v_pk_fma_f32 v[6:7], v[32:33], v[80:81], v[6:7]
	s_mov_b64 exec, s[6:7]
	v_lshlrev_b32_e32 v42, 16, v168
	v_and_b32_e32 v43, 0xffff0000, v168
	v_lshlrev_b32_e32 v44, 16, v169
	v_and_b32_e32 v45, 0xffff0000, v169
	s_waitcnt lgkmcnt(0)
	v_pk_fma_f32 v[0:1], v[34:35], v[42:43], v[0:1]
	v_pk_fma_f32 v[2:3], v[36:37], v[44:45], v[2:3]
	v_lshlrev_b32_e32 v46, 16, v170
	v_and_b32_e32 v47, 0xffff0000, v170
	v_lshlrev_b32_e32 v80, 16, v171
	v_and_b32_e32 v81, 0xffff0000, v171
	v_pk_fma_f32 v[4:5], v[38:39], v[46:47], v[4:5]
	v_pk_fma_f32 v[6:7], v[40:41], v[80:81], v[6:7]
	s_mov_b64 exec, -1
	v_cvt_pk_bf16_f32 v68, v0, v1
	v_cvt_pk_bf16_f32 v69, v2, v3
	v_cvt_pk_bf16_f32 v70, v4, v5
	v_cvt_pk_bf16_f32 v71, v6, v7
	s_waitcnt lgkmcnt(3)
	s_waitcnt lgkmcnt(1)
	s_waitcnt lgkmcnt(0)
	s_nop 0
	s_waitcnt vmcnt(4)
	s_waitcnt vmcnt(4)
	s_waitcnt lgkmcnt(3)
	s_waitcnt lgkmcnt(1)
	s_waitcnt lgkmcnt(0)
	s_waitcnt vmcnt(4)
	s_waitcnt vmcnt(4)
	ds_read_b128 v[0:3], v9 offset:10624
	ds_read_b128 v[4:7], v9 offset:10640
	ds_read_b128 v[26:29], v9 offset:8576
	ds_read_b128 v[30:33], v9 offset:8592
	ds_read_b128 v[34:37], v9 offset:9088
	ds_read_b128 v[38:41], v9 offset:9104
	s_mov_b64 exec, vcc
	v_lshlrev_b32_e32 v42, 16, v178
	v_and_b32_e32 v43, 0xffff0000, v178
	v_lshlrev_b32_e32 v44, 16, v179
	v_and_b32_e32 v45, 0xffff0000, v179
	s_waitcnt lgkmcnt(2)
	v_pk_fma_f32 v[0:1], v[26:27], v[42:43], v[0:1]
	v_pk_fma_f32 v[2:3], v[28:29], v[44:45], v[2:3]
	v_lshlrev_b32_e32 v46, 16, v180
	v_and_b32_e32 v47, 0xffff0000, v180
	v_lshlrev_b32_e32 v80, 16, v181
	v_and_b32_e32 v81, 0xffff0000, v181
	v_pk_fma_f32 v[4:5], v[30:31], v[46:47], v[4:5]
	v_pk_fma_f32 v[6:7], v[32:33], v[80:81], v[6:7]
	s_mov_b64 exec, -1
	ds_read_b128 v[26:29], v9 offset:9600
	ds_read_b128 v[30:33], v9 offset:9616
	s_mov_b64 exec, s[4:5]
	v_lshlrev_b32_e32 v42, 16, v182
	v_and_b32_e32 v43, 0xffff0000, v182
	v_lshlrev_b32_e32 v44, 16, v183
	v_and_b32_e32 v45, 0xffff0000, v183
	s_waitcnt lgkmcnt(2)
	v_pk_fma_f32 v[0:1], v[34:35], v[42:43], v[0:1]
	v_pk_fma_f32 v[2:3], v[36:37], v[44:45], v[2:3]
	v_lshlrev_b32_e32 v46, 16, v184
	v_and_b32_e32 v47, 0xffff0000, v184
	v_lshlrev_b32_e32 v80, 16, v185
	v_and_b32_e32 v81, 0xffff0000, v185
	v_pk_fma_f32 v[4:5], v[38:39], v[46:47], v[4:5]
	v_pk_fma_f32 v[6:7], v[40:41], v[80:81], v[6:7]
	s_mov_b64 exec, -1
	ds_read_b128 v[34:37], v9 offset:10112
	ds_read_b128 v[38:41], v9 offset:10128
	v_lshlrev_b32_e32 v42, 16, v186
	v_and_b32_e32 v43, 0xffff0000, v186
	v_lshlrev_b32_e32 v44, 16, v187
	v_and_b32_e32 v45, 0xffff0000, v187
	s_waitcnt lgkmcnt(2)
	v_pk_fma_f32 v[0:1], v[26:27], v[42:43], v[0:1]
	v_pk_fma_f32 v[2:3], v[28:29], v[44:45], v[2:3]
	v_lshlrev_b32_e32 v46, 16, v188
	v_and_b32_e32 v47, 0xffff0000, v188
	v_lshlrev_b32_e32 v80, 16, v189
	v_and_b32_e32 v81, 0xffff0000, v189
	v_pk_fma_f32 v[4:5], v[30:31], v[46:47], v[4:5]
	v_pk_fma_f32 v[6:7], v[32:33], v[80:81], v[6:7]
	s_mov_b64 exec, s[6:7]
	v_lshlrev_b32_e32 v42, 16, v190
	v_and_b32_e32 v43, 0xffff0000, v190
	v_lshlrev_b32_e32 v44, 16, v191
	v_and_b32_e32 v45, 0xffff0000, v191
	s_waitcnt lgkmcnt(0)
	v_pk_fma_f32 v[0:1], v[34:35], v[42:43], v[0:1]
	v_pk_fma_f32 v[2:3], v[36:37], v[44:45], v[2:3]
	v_lshlrev_b32_e32 v46, 16, v192
	v_and_b32_e32 v47, 0xffff0000, v192
	v_lshlrev_b32_e32 v80, 16, v193
	v_and_b32_e32 v81, 0xffff0000, v193
	v_pk_fma_f32 v[4:5], v[38:39], v[46:47], v[4:5]
	v_pk_fma_f32 v[6:7], v[40:41], v[80:81], v[6:7]
	s_mov_b64 exec, -1
	v_cvt_pk_bf16_f32 v72, v0, v1
	v_cvt_pk_bf16_f32 v73, v2, v3
	v_cvt_pk_bf16_f32 v74, v4, v5
	v_cvt_pk_bf16_f32 v75, v6, v7
	s_waitcnt lgkmcnt(3)
	s_waitcnt lgkmcnt(1)
	s_waitcnt lgkmcnt(0)
	v_lshlrev_b32_e32 v38, 3, v92
	s_nop 0
	s_nop 0
	v_or_b32_e32 v39, 16, v38
	s_waitcnt vmcnt(0)
	s_waitcnt vmcnt(0)
	s_waitcnt lgkmcnt(3)
	s_waitcnt lgkmcnt(1)
	s_waitcnt lgkmcnt(0)
	s_waitcnt vmcnt(0)
	s_waitcnt vmcnt(0)
	ds_read_b128 v[0:3], v9 offset:10688
	ds_read_b128 v[4:7], v9 offset:10704
	ds_read_b128 v[26:29], v9 offset:8640
	ds_read_b128 v[30:33], v9 offset:8656
	ds_read_b128 v[34:37], v9 offset:9152
	ds_read_b128 v[40:43], v9 offset:9168
	s_mov_b64 exec, vcc
	v_lshlrev_b32_e32 v44, 16, v194
	v_and_b32_e32 v45, 0xffff0000, v194
	v_lshlrev_b32_e32 v46, 16, v195
	v_and_b32_e32 v47, 0xffff0000, v195
	s_waitcnt lgkmcnt(2)
	v_pk_fma_f32 v[0:1], v[26:27], v[44:45], v[0:1]
	v_pk_fma_f32 v[2:3], v[28:29], v[46:47], v[2:3]
	v_lshlrev_b32_e32 v80, 16, v196
	v_and_b32_e32 v81, 0xffff0000, v196
	v_lshlrev_b32_e32 v82, 16, v197
	v_and_b32_e32 v83, 0xffff0000, v197
	v_pk_fma_f32 v[4:5], v[30:31], v[80:81], v[4:5]
	v_pk_fma_f32 v[6:7], v[32:33], v[82:83], v[6:7]
	s_mov_b64 exec, -1
	ds_read_b128 v[26:29], v9 offset:9664
	ds_read_b128 v[30:33], v9 offset:9680
	s_mov_b64 exec, s[4:5]
	v_lshlrev_b32_e32 v44, 16, v198
	v_and_b32_e32 v45, 0xffff0000, v198
	v_lshlrev_b32_e32 v46, 16, v199
	v_and_b32_e32 v47, 0xffff0000, v199
	s_waitcnt lgkmcnt(2)
	v_pk_fma_f32 v[0:1], v[34:35], v[44:45], v[0:1]
	v_pk_fma_f32 v[2:3], v[36:37], v[46:47], v[2:3]
	v_lshlrev_b32_e32 v80, 16, v200
	v_and_b32_e32 v81, 0xffff0000, v200
	v_lshlrev_b32_e32 v82, 16, v201
	v_and_b32_e32 v83, 0xffff0000, v201
	v_pk_fma_f32 v[4:5], v[40:41], v[80:81], v[4:5]
	v_pk_fma_f32 v[6:7], v[42:43], v[82:83], v[6:7]
	s_mov_b64 exec, -1
	ds_read_b128 v[34:37], v9 offset:10176
	ds_read_b128 v[40:43], v9 offset:10192
	v_lshlrev_b32_e32 v44, 16, v202
	v_and_b32_e32 v45, 0xffff0000, v202
	v_lshlrev_b32_e32 v46, 16, v203
	v_and_b32_e32 v47, 0xffff0000, v203
	s_waitcnt lgkmcnt(2)
	v_pk_fma_f32 v[0:1], v[26:27], v[44:45], v[0:1]
	v_pk_fma_f32 v[2:3], v[28:29], v[46:47], v[2:3]
	v_lshlrev_b32_e32 v80, 16, v204
	v_and_b32_e32 v81, 0xffff0000, v204
	v_lshlrev_b32_e32 v82, 16, v205
	v_and_b32_e32 v83, 0xffff0000, v205
	v_pk_fma_f32 v[4:5], v[30:31], v[80:81], v[4:5]
	v_pk_fma_f32 v[6:7], v[32:33], v[82:83], v[6:7]
	s_mov_b64 exec, s[6:7]
	v_lshlrev_b32_e32 v44, 16, v206
	v_and_b32_e32 v45, 0xffff0000, v206
	v_lshlrev_b32_e32 v46, 16, v207
	v_and_b32_e32 v47, 0xffff0000, v207
	s_waitcnt lgkmcnt(0)
	v_pk_fma_f32 v[0:1], v[34:35], v[44:45], v[0:1]
	v_pk_fma_f32 v[2:3], v[36:37], v[46:47], v[2:3]
	v_lshlrev_b32_e32 v80, 16, v208
	v_and_b32_e32 v81, 0xffff0000, v208
	v_lshlrev_b32_e32 v82, 16, v209
	v_and_b32_e32 v83, 0xffff0000, v209
	v_pk_fma_f32 v[4:5], v[40:41], v[80:81], v[4:5]
	v_pk_fma_f32 v[6:7], v[42:43], v[82:83], v[6:7]
	s_mov_b64 exec, -1
	v_cvt_pk_bf16_f32 v76, v0, v1
	v_cvt_pk_bf16_f32 v77, v2, v3
	v_cvt_pk_bf16_f32 v78, v4, v5
	v_cvt_pk_bf16_f32 v79, v6, v7
	s_waitcnt lgkmcnt(3)
	s_waitcnt lgkmcnt(1)
	s_waitcnt lgkmcnt(0)
	v_cmp_eq_u32_e32 vcc, v38, v93
	v_or_b32_e32 v2, 1, v38
	v_cndmask_b32_e32 v0, 0, v128, vcc
	v_or_b32_e32 v1, 2, v38
	v_cmp_eq_u32_e32 vcc, v2, v93
	v_or_b32_e32 v4, 3, v38
	v_or_b32_e32 v3, 4, v38
	v_cndmask_b32_e32 v2, 0, v128, vcc
	v_cmp_eq_u32_e32 vcc, v1, v93
	v_or_b32_e32 v5, 6, v38
	v_or_b32_e32 v6, 5, v38
	v_cndmask_b32_e32 v1, 0, v128, vcc
	v_cmp_eq_u32_e32 vcc, v4, v93
	v_or_b32_e32 v7, 7, v38
	v_or_b32_e32 v11, 17, v38
	v_cndmask_b32_e32 v4, 0, v128, vcc
	v_cmp_eq_u32_e32 vcc, v3, v93
	v_or_b32_e32 v10, 18, v38
	v_or_b32_e32 v13, 19, v38
	v_cndmask_b32_e32 v3, 0, v128, vcc
	v_cmp_eq_u32_e32 vcc, v5, v93
	v_or_b32_e32 v12, 20, v38
	v_or_b32_e32 v14, 22, v38
	v_cndmask_b32_e32 v5, 0, v128, vcc
	v_cmp_eq_u32_e32 vcc, v6, v93
	v_or_b32_e32 v15, 21, v38
	v_or_b32_e32 v16, 23, v38
	v_cndmask_b32_e32 v6, 0, v128, vcc
	v_cmp_eq_u32_e32 vcc, v7, v93
	v_and_b32_e32 v18, 64, v126
	v_xor_b32_e32 v17, 32, v126
	v_cndmask_b32_e32 v7, 0, v128, vcc
	v_cmp_eq_u32_e32 vcc, v39, v93
	v_add_u32_e32 v18, 64, v18
	s_lshl_b32 s6, s64, 8
	v_cndmask_b32_e32 v9, 0, v128, vcc
	v_cmp_eq_u32_e32 vcc, v11, v93
	s_add_i32 s6, s6, 16
	v_cmp_eq_u32_e64 s[4:5], 0, v92
	v_cndmask_b32_e32 v11, 0, v128, vcc
	v_cmp_eq_u32_e32 vcc, v10, v93
	v_lshl_add_u32 v136, v93, 3, s6
	v_perm_b32 v82, v6, v3, s87
	v_cndmask_b32_e32 v10, 0, v128, vcc
	v_cmp_eq_u32_e32 vcc, v13, v93
	v_perm_b32 v81, v4, v1, s87
	v_perm_b32 v83, v7, v5, s87
	v_cndmask_b32_e32 v13, 0, v128, vcc
	v_cmp_eq_u32_e32 vcc, v12, v93
	v_perm_b32 v80, v2, v0, s87
	v_perm_b32 v85, v13, v10, s87
	v_cndmask_b32_e32 v12, 0, v128, vcc
	v_cmp_eq_u32_e32 vcc, v14, v93
	v_perm_b32 v84, v11, v9, s87
	s_nop 0
	v_cndmask_b32_e32 v14, 0, v128, vcc
	v_cmp_eq_u32_e32 vcc, v15, v93
	s_nop 1
	v_cndmask_b32_e32 v15, 0, v128, vcc
	v_cmp_eq_u32_e32 vcc, v16, v93
	v_perm_b32 v86, v15, v12, s87
	s_nop 0
	v_cndmask_b32_e32 v16, 0, v128, vcc
	v_cmp_lt_i32_e32 vcc, v17, v18
	v_perm_b32 v87, v16, v14, s87
	s_nop 0
	v_cndmask_b32_e32 v17, v126, v17, vcc
	v_lshlrev_b32_e32 v137, 2, v17
	v_lshl_or_b32 v175, v138, 2, v129
	global_load_dword v172, v175, s[42:43]
	global_load_dword v173, v175, s[36:37]
	global_load_dword v174, v175, s[40:41]
	s_setprio 1
	v_xad_u32 v145, v88, v8, v94
	ds_read_b128 v[0:3], v145 offset:16384
	ds_read_b128 v[4:7], v145 offset:49152
	s_waitcnt lgkmcnt(1)
	v_mfma_f32_32x32x16_bf16 v[32:47], v[48:51], v[0:3], 0
	v_or_b32_e32 v0, 32, v88
	v_xad_u32 v147, v0, v8, v94
	s_waitcnt lgkmcnt(0)
	v_mfma_f32_32x32x16_bf16 v[16:31], v[48:51], v[4:7], 0
	ds_read_b128 v[0:3], v147 offset:16384
	ds_read_b128 v[4:7], v147 offset:49152
	s_waitcnt lgkmcnt(1)
	v_mfma_f32_32x32x16_bf16 v[32:47], v[52:55], v[0:3], v[32:47]
	v_or_b32_e32 v0, 64, v88
	v_xad_u32 v142, v0, v8, v94
	s_waitcnt lgkmcnt(0)
	v_mfma_f32_32x32x16_bf16 v[16:31], v[52:55], v[4:7], v[16:31]
	ds_read_b128 v[0:3], v142 offset:16384
	ds_read_b128 v[4:7], v142 offset:49152
	s_waitcnt lgkmcnt(1)
	v_mfma_f32_32x32x16_bf16 v[32:47], v[56:59], v[0:3], v[32:47]
	v_or_b32_e32 v0, 0x60, v88
	v_xad_u32 v146, v0, v8, v94
	s_waitcnt lgkmcnt(0)
	v_mfma_f32_32x32x16_bf16 v[16:31], v[56:59], v[4:7], v[16:31]
	ds_read_b128 v[0:3], v146 offset:16384
	ds_read_b128 v[4:7], v146 offset:49152
	s_waitcnt lgkmcnt(1)
	v_mfma_f32_32x32x16_bf16 v[32:47], v[60:63], v[0:3], v[32:47]
	v_or_b32_e32 v0, 0x80, v88
	v_xad_u32 v141, v0, v8, v94
	s_waitcnt lgkmcnt(0)
	v_mfma_f32_32x32x16_bf16 v[16:31], v[60:63], v[4:7], v[16:31]
	ds_read_b128 v[0:3], v141 offset:16384
	ds_read_b128 v[4:7], v141 offset:49152
	s_waitcnt lgkmcnt(1)
	v_mfma_f32_32x32x16_bf16 v[32:47], v[64:67], v[0:3], v[32:47]
	v_or_b32_e32 v0, 0xa0, v88
	v_xad_u32 v144, v0, v8, v94
	s_waitcnt lgkmcnt(0)
	v_mfma_f32_32x32x16_bf16 v[16:31], v[64:67], v[4:7], v[16:31]
	ds_read_b128 v[0:3], v144 offset:16384
	ds_read_b128 v[4:7], v144 offset:49152
	s_waitcnt lgkmcnt(1)
	v_mfma_f32_32x32x16_bf16 v[32:47], v[68:71], v[0:3], v[32:47]
	v_or_b32_e32 v0, 0xc0, v88
	v_xad_u32 v139, v0, v8, v94
	s_waitcnt lgkmcnt(0)
	v_mfma_f32_32x32x16_bf16 v[16:31], v[68:71], v[4:7], v[16:31]
	ds_read_b128 v[0:3], v139 offset:16384
	ds_read_b128 v[4:7], v139 offset:49152
	s_waitcnt lgkmcnt(1)
	v_mfma_f32_32x32x16_bf16 v[32:47], v[72:75], v[0:3], v[32:47]
	v_or_b32_e32 v0, 0xe0, v88
	v_xad_u32 v143, v0, v8, v94
	s_waitcnt lgkmcnt(0)
	v_mfma_f32_32x32x16_bf16 v[16:31], v[72:75], v[4:7], v[16:31]
	ds_read_b128 v[0:3], v143 offset:16384
	ds_read_b128 v[4:7], v143 offset:49152
	s_waitcnt lgkmcnt(1)
	v_mfma_f32_32x32x16_bf16 v[32:47], v[76:79], v[0:3], v[32:47]
	s_waitcnt lgkmcnt(0)
	v_mfma_f32_32x32x16_bf16 v[16:31], v[76:79], v[4:7], v[16:31]
	v_mfma_f32_32x32x16_bf16 v[0:15], v[48:51], v[80:83], 0
	v_mfma_f32_32x32x16_bf16 v[0:15], v[52:55], v[84:87], v[0:15]
	s_setprio 0
	v_lshl_or_b32 v88, v138, 2, v129
	s_waitcnt vmcnt(0)
	ds_read_b32 v251, v167
	v_mul_f32_e32 v94, 0xbfb8aa3b, v173
	v_mul_f32_e32 v88, 0xbfb8aa3b, v174
	v_fmamk_f32 v32, v32, 0xbfb8aa3b, v94
	v_fmamk_f32 v16, v16, 0xbfb8aa3b, v88
	v_exp_f32_e32 v32, v32
	v_exp_f32_e32 v96, v16
	v_fmamk_f32 v17, v17, 0xbfb8aa3b, v88
	v_exp_f32_e32 v97, v17
	v_add_f32_e32 v32, 1.0, v32
	v_add_f32_e32 v96, 1.0, v96
	v_rcp_f32_e32 v17, v32
	v_rcp_f32_e32 v32, v96
	v_fmamk_f32 v33, v33, 0xbfb8aa3b, v94
	v_fmamk_f32 v34, v34, 0xbfb8aa3b, v94
	v_exp_f32_e32 v33, v33
	v_exp_f32_e32 v34, v34
	v_add_f32_e32 v33, 1.0, v33
	v_add_f32_e32 v34, 1.0, v34
	v_rcp_f32_e32 v33, v33
	v_rcp_f32_e32 v34, v34
	v_fmamk_f32 v18, v18, 0xbfb8aa3b, v88
	v_fmamk_f32 v19, v19, 0xbfb8aa3b, v88
	v_exp_f32_e32 v18, v18
	s_waitcnt lgkmcnt(0)
	v_mul_f32_e32 v95, 0x3fb8aa3b, v251
	v_mul_f32_e32 v16, v17, v95
	v_mul_f32_e32 v17, v33, v95
	v_exp_f32_e32 v33, v16
	v_mul_f32_e32 v16, v34, v95
	v_exp_f32_e32 v98, v16
	v_fmamk_f32 v16, v35, 0xbfb8aa3b, v94
	v_exp_f32_e32 v16, v16
	v_exp_f32_e32 v96, v17
	v_add_f32_e32 v16, 1.0, v16
	v_rcp_f32_e32 v16, v16
	v_exp_f32_e32 v19, v19
	v_add_f32_e32 v97, 1.0, v97
	v_add_f32_e32 v18, 1.0, v18
	v_mul_f32_e32 v16, v16, v95
	v_exp_f32_e32 v16, v16
	v_fma_f32 v35, -v98, v98, 1.0
	v_rcp_f32_e32 v17, v97
	v_fma_f32 v34, -v33, v33, 1.0
	v_fma_f32 v97, -v96, v96, 1.0
	v_rcp_f32_e32 v18, v18
	v_sqrt_f32_e32 v35, v35
	v_add_f32_e32 v19, 1.0, v19
	v_fma_f32 v99, -v16, v16, 1.0
	v_sqrt_f32_e32 v34, v34
	v_sqrt_f32_e32 v97, v97
	v_rcp_f32_e32 v19, v19
	v_sqrt_f32_e32 v99, v99
	v_mul_f32_e32 v35, v18, v35
	v_fmamk_f32 v18, v36, 0xbfb8aa3b, v94
	v_mul_f32_e32 v32, v32, v34
	v_mul_f32_e32 v34, v17, v97
	v_mul_f32_e32 v17, v19, v99
	v_fmamk_f32 v19, v20, 0xbfb8aa3b, v88
	v_exp_f32_e32 v18, v18
	v_exp_f32_e32 v19, v19
	v_mul_f32_e32 v3, v3, v17
	v_add_f32_e32 v17, 1.0, v18
	v_rcp_f32_e32 v17, v17
	v_add_f32_e32 v18, 1.0, v19
	v_fmamk_f32 v19, v37, 0xbfb8aa3b, v94
	v_exp_f32_e32 v19, v19
	v_mul_f32_e32 v17, v17, v95
	v_exp_f32_e32 v36, v17
	v_add_f32_e32 v17, 1.0, v19
	v_rcp_f32_e32 v17, v17
	v_fmamk_f32 v19, v21, 0xbfb8aa3b, v88
	v_exp_f32_e32 v19, v19
	v_mul_f32_e32 v17, v17, v95
	v_exp_f32_e32 v37, v17
	v_fmamk_f32 v17, v38, 0xbfb8aa3b, v94
	v_exp_f32_e32 v17, v17
	v_fmamk_f32 v23, v23, 0xbfb8aa3b, v88
	v_add_f32_e32 v19, 1.0, v19
	v_fma_f32 v21, -v37, v37, 1.0
	v_add_f32_e32 v17, 1.0, v17
	v_rcp_f32_e32 v17, v17
	v_rcp_f32_e32 v19, v19
	v_sqrt_f32_e32 v21, v21
	v_mul_f32_e32 v17, v17, v95
	v_exp_f32_e32 v38, v17
	v_fmamk_f32 v17, v39, 0xbfb8aa3b, v94
	v_exp_f32_e32 v17, v17
	v_exp_f32_e32 v23, v23
	v_fma_f32 v20, -v36, v36, 1.0
	v_mul_f32_e32 v100, v19, v21
	v_add_f32_e32 v17, 1.0, v17
	v_rcp_f32_e32 v17, v17
	v_add_f32_e32 v23, 1.0, v23
	v_fmamk_f32 v19, v40, 0xbfb8aa3b, v94
	v_rcp_f32_e32 v18, v18
	v_mul_f32_e32 v17, v17, v95
	v_exp_f32_e32 v17, v17
	v_sqrt_f32_e32 v20, v20
	v_rcp_f32_e32 v23, v23
	v_fma_f32 v97, -v17, v17, 1.0
	v_sqrt_f32_e32 v97, v97
	v_fmamk_f32 v21, v24, 0xbfb8aa3b, v88
	v_fmamk_f32 v22, v22, 0xbfb8aa3b, v88
	v_exp_f32_e32 v19, v19
	v_exp_f32_e32 v21, v21
	v_exp_f32_e32 v22, v22
	v_mul_f32_e32 v99, v18, v20
	v_mul_f32_e32 v18, v23, v97
	v_mul_f32_e32 v7, v7, v18
	v_add_f32_e32 v18, 1.0, v19
	v_rcp_f32_e32 v18, v18
	v_add_f32_e32 v19, 1.0, v21
	v_fmamk_f32 v21, v41, 0xbfb8aa3b, v94
	v_add_f32_e32 v22, 1.0, v22
	v_fma_f32 v39, -v38, v38, 1.0
	v_rcp_f32_e32 v22, v22
	v_sqrt_f32_e32 v39, v39
	v_exp_f32_e32 v21, v21
	v_mul_f32_e32 v18, v18, v95
	v_mul_f32_e32 v20, v22, v39
	v_exp_f32_e32 v39, v18
	v_add_f32_e32 v18, 1.0, v21
	v_rcp_f32_e32 v18, v18
	v_fmamk_f32 v21, v25, 0xbfb8aa3b, v88
	v_exp_f32_e32 v21, v21
	v_mul_f32_e32 v18, v18, v95
	v_exp_f32_e32 v40, v18
	v_fmamk_f32 v18, v42, 0xbfb8aa3b, v94
	v_exp_f32_e32 v18, v18
	v_fmamk_f32 v24, v26, 0xbfb8aa3b, v88
	v_fmamk_f32 v26, v27, 0xbfb8aa3b, v88
	v_add_f32_e32 v21, 1.0, v21
	v_add_f32_e32 v18, 1.0, v18
	v_rcp_f32_e32 v18, v18
	v_fma_f32 v23, -v40, v40, 1.0
	v_fma_f32 v22, -v39, v39, 1.0
	v_mul_f32_e32 v18, v18, v95
	v_exp_f32_e32 v41, v18
	v_fmamk_f32 v18, v43, 0xbfb8aa3b, v94
	v_exp_f32_e32 v18, v18
	v_rcp_f32_e32 v21, v21
	v_sqrt_f32_e32 v23, v23
	v_exp_f32_e32 v26, v26
	v_add_f32_e32 v18, 1.0, v18
	v_rcp_f32_e32 v18, v18
	v_rcp_f32_e32 v19, v19
	v_sqrt_f32_e32 v22, v22
	v_add_f32_e32 v26, 1.0, v26
	v_mul_f32_e32 v18, v18, v95
	v_exp_f32_e32 v18, v18
	v_mul_f32_e32 v43, v21, v23
	v_fmamk_f32 v21, v44, 0xbfb8aa3b, v94
	v_rcp_f32_e32 v26, v26
	v_fma_f32 v27, -v18, v18, 1.0
	v_sqrt_f32_e32 v27, v27
	v_mul_f32_e32 v42, v19, v22
	v_fmamk_f32 v22, v28, 0xbfb8aa3b, v88
	v_exp_f32_e32 v21, v21
	v_exp_f32_e32 v22, v22
	v_mul_f32_e32 v19, v26, v27
	v_mul_f32_e32 v11, v11, v19
	v_add_f32_e32 v19, 1.0, v21
	v_rcp_f32_e32 v19, v19
	v_add_f32_e32 v21, 1.0, v22
	v_fmamk_f32 v22, v45, 0xbfb8aa3b, v94
	v_exp_f32_e32 v22, v22
	v_mul_f32_e32 v19, v19, v95
	v_exp_f32_e32 v44, v19
	v_add_f32_e32 v19, 1.0, v22
	v_rcp_f32_e32 v19, v19
	v_exp_f32_e32 v24, v24
	v_fma_f32 v25, -v41, v41, 1.0
	v_mul_f32_e32 v19, v19, v95
	v_exp_f32_e32 v45, v19
	v_fmamk_f32 v19, v46, 0xbfb8aa3b, v94
	v_exp_f32_e32 v19, v19
	v_add_f32_e32 v24, 1.0, v24
	v_rcp_f32_e32 v24, v24
	v_sqrt_f32_e32 v25, v25
	v_add_f32_e32 v19, 1.0, v19
	v_rcp_f32_e32 v19, v19
	v_fmamk_f32 v22, v29, 0xbfb8aa3b, v88
	v_mul_f32_e32 v97, v24, v25
	v_fma_f32 v24, -v45, v45, 1.0
	v_mul_f32_e32 v19, v19, v95
	v_exp_f32_e32 v46, v19
	v_fmamk_f32 v19, v47, 0xbfb8aa3b, v94
	v_exp_f32_e32 v19, v19
	v_sqrt_f32_e32 v25, v24
	v_fmamk_f32 v24, v30, 0xbfb8aa3b, v88
	v_exp_f32_e32 v24, v24
	v_add_f32_e32 v19, 1.0, v19
	v_rcp_f32_e32 v19, v19
	v_fma_f32 v27, -v46, v46, 1.0
	v_add_f32_e32 v24, 1.0, v24
	v_rcp_f32_e32 v26, v24
	v_fmamk_f32 v24, v31, 0xbfb8aa3b, v88
	v_mul_f32_e32 v19, v19, v95
	v_exp_f32_e32 v28, v24
	v_exp_f32_e32 v24, v19
	v_sqrt_f32_e32 v19, v27
	v_add_f32_e32 v27, 1.0, v28
	v_fma_f32 v28, -v24, v24, 1.0
	v_exp_f32_e32 v22, v22
	v_rcp_f32_e32 v27, v27
	v_sqrt_f32_e32 v28, v28
	v_fma_f32 v23, -v44, v44, 1.0
	v_rcp_f32_e32 v21, v21
	v_sqrt_f32_e32 v23, v23
	v_add_f32_e32 v22, 1.0, v22
	v_mul_f32_e32 v94, v26, v19
	v_mul_f32_e32 v19, v27, v28
	v_fmac_f32_e32 v7, 0, v17
	v_rcp_f32_e32 v22, v22
	v_mul_f32_e32 v15, v15, v19
	v_mul_f32_e32 v19, v38, v7
	v_fmac_f32_e32 v3, 0, v16
	v_fmac_f32_e32 v19, v6, v20
	v_mul_f32_e32 v47, v21, v23
	v_mul_f32_e32 v21, v98, v3
	v_mul_f32_e32 v20, v37, v19
	v_fmac_f32_e32 v15, 0, v24
	v_fmac_f32_e32 v21, v2, v35
	v_fmac_f32_e32 v20, v5, v100
	v_mul_f32_e32 v2, v46, v15
	v_mul_f32_e32 v88, v22, v25
	v_mul_f32_e32 v22, v36, v20
	v_fmac_f32_e32 v2, v14, v94
	v_fmac_f32_e32 v22, v4, v99
	v_mul_f32_e32 v4, v45, v2
	v_mul_f32_e32 v23, v96, v21
	v_fmac_f32_e32 v4, v13, v88
	v_fmac_f32_e32 v23, v1, v34
	v_fmac_f32_e32 v11, 0, v18
	v_mul_f32_e32 v14, v24, v46
	v_mul_f32_e32 v6, v44, v4
	v_mul_f32_e32 v25, v33, v23
	v_mul_f32_e32 v5, v41, v11
	v_mul_f32_e32 v13, v45, v14
	v_fmac_f32_e32 v6, v12, v47
	v_fmac_f32_e32 v25, v0, v32
	v_fmac_f32_e32 v5, v10, v97
	v_mul_f32_e32 v12, v44, v13
	ds_bpermute_b32 v0, v137, v6
	v_mul_f32_e32 v10, v40, v5
	ds_bpermute_b32 v35, v137, v12
	v_mul_f32_e32 v28, v18, v41
	v_fmac_f32_e32 v10, v9, v43
	v_mul_f32_e32 v26, v16, v98
	v_mul_f32_e32 v27, v17, v38
	v_mul_f32_e32 v31, v40, v28
	v_mul_f32_e32 v9, v39, v10
	v_mul_f32_e32 v29, v96, v26
	v_mul_f32_e32 v30, v37, v27
	v_fmac_f32_e32 v9, v8, v42
	v_mul_f32_e32 v34, v39, v31
	v_mul_f32_e32 v32, v33, v29
	v_mul_f32_e32 v33, v36, v30
	s_waitcnt lgkmcnt(1)
	v_cndmask_b32_e64 v36, v0, v6, s[4:5]
	v_cndmask_b32_e64 v37, v6, v0, s[4:5]
	ds_bpermute_b32 v0, v137, v34
	ds_bpermute_b32 v40, v137, v9
	s_waitcnt lgkmcnt(2)
	v_cndmask_b32_e64 v8, v12, v35, s[4:5]
	v_fmac_f32_e32 v37, 0, v8
	ds_bpermute_b32 v8, v137, v33
	v_cndmask_b32_e64 v1, v35, v12, s[4:5]
	v_mul_f32_e32 v38, v12, v35
	v_fmac_f32_e32 v36, v1, v37
	s_waitcnt lgkmcnt(2)
	v_cndmask_b32_e64 v1, v0, v34, s[4:5]
	s_waitcnt lgkmcnt(1)
	v_cndmask_b32_e64 v39, v40, v9, s[4:5]
	v_cndmask_b32_e64 v0, v34, v0, s[4:5]
	v_cndmask_b32_e64 v40, v9, v40, s[4:5]
	ds_bpermute_b32 v44, v137, v22
	v_mul_f32_e32 v41, v38, v0
	v_fmac_f32_e32 v40, v0, v36
	v_mul_f32_e32 v42, v1, v41
	v_fmac_f32_e32 v39, v1, v40
	s_waitcnt lgkmcnt(1)
	v_cndmask_b32_e64 v0, v8, v33, s[4:5]
	v_cndmask_b32_e64 v1, v33, v8, s[4:5]
	ds_bpermute_b32 v8, v137, v32
	ds_bpermute_b32 v47, v137, v25
	s_waitcnt lgkmcnt(2)
	v_cndmask_b32_e64 v43, v44, v22, s[4:5]
	v_cndmask_b32_e64 v44, v22, v44, s[4:5]
	v_mul_f32_e32 v45, v1, v42
	v_fmac_f32_e32 v44, v1, v39
	v_mul_f32_e32 v46, v0, v45
	v_fmac_f32_e32 v43, v0, v44
	s_waitcnt lgkmcnt(1)
	v_cndmask_b32_e64 v0, v32, v8, s[4:5]
	s_waitcnt lgkmcnt(0)
	v_cndmask_b32_e64 v47, v25, v47, s[4:5]
	v_mul_f32_e32 v88, v0, v46
	v_fmac_f32_e32 v47, v0, v43
	s_and_saveexec_b64 s[6:7], s[4:5]
	v_mul_f32_e32 v0, v32, v88
	v_fma_f32 v1, v32, v47, v25
	ds_write_b64 v136, v[0:1]
	s_or_b64 exec, exec, s[6:7]
	s_cmp_lt_i32 s64, 7
	s_cselect_b64 s[14:15], -1, 0
	s_cmp_gt_i32 s64, 6
	v_mul_i32_i24_e32 v140, 0xffffff08, v93
	s_waitcnt lgkmcnt(0)
	s_barrier
	s_cbranch_scc1 .LBB0_269
	v_add3_u32 v94, v140, v91, s92
	v_mov_b32_e32 v8, 1.0
	v_mov_b32_e32 v1, 0
	s_mov_b32 s6, 7

.LBB0_301:
	v_mov_b32_e32 v92, v177
	s_andn2_b64 vcc, exec, s[0:1]
	v_readfirstlane_b32 s89, v92
	s_waitcnt vmcnt(4)
	v_lshlrev_b32_e32 v8, 4, v92
	s_barrier
	s_cbranch_vccnz .LBB0_320
	s_waitcnt vmcnt(0)
	v_mul_f32_e32 v91, 0xbfb8aa3b, v91
	v_exp_f32_e32 v160, v91
	s_nop 0
	v_add_f32_e32 v35, 1.0, v160
	v_frexp_mant_f32_e32 v154, v35
	v_cvt_f64_f32_e32 v[16:17], v35
	v_add_f32_e32 v153, -1.0, v35
	v_frexp_exp_i32_f64_e32 v16, v[16:17]
	v_cmp_gt_f32_e32 vcc, s84, v154
	v_sub_f32_e32 v34, v153, v35
	v_subbrev_co_u32_e32 v16, vcc, 0, v16, vcc
	v_sub_f32_e32 v153, v160, v153
	v_add_f32_e32 v17, 1.0, v34
	v_sub_u32_e32 v32, 0, v16
	v_add_f32_e32 v17, v153, v17
	v_ldexp_f32 v33, v35, v32
	v_ldexp_f32 v17, v17, v32
	v_add_f32_e32 v32, -1.0, v33
	v_add_f32_e32 v34, 1.0, v33
	v_add_f32_e32 v35, 1.0, v32
	v_add_f32_e32 v91, -1.0, v34
	v_sub_f32_e32 v35, v33, v35
	v_sub_f32_e32 v33, v33, v91
	v_add_f32_e32 v35, v17, v35
	v_add_f32_e32 v17, v17, v33
	v_add_f32_e32 v91, v34, v17
	v_rcp_f32_e32 v154, v91
	v_add_f32_e32 v33, v32, v35
	v_sub_f32_e32 v34, v91, v34
	v_mul_f32_e32 v156, v33, v154
	v_sub_f32_e32 v17, v17, v34
	v_mul_f32_e32 v34, v91, v156
	v_fma_f32 v152, v156, v91, -v34
	v_sub_f32_e32 v32, v33, v32
	v_fmac_f32_e32 v152, v156, v17
	v_sub_f32_e32 v155, v35, v32
	v_add_f32_e32 v32, v34, v152
	v_sub_f32_e32 v35, v33, v32
	v_mov_b32_e32 v153, v32
	v_pk_add_f32 v[32:33], v[32:33], v[34:35] neg_lo:[0,1] neg_hi:[0,1]
	v_cvt_f32_i32_e32 v16, v16
	v_pk_add_f32 v[32:33], v[32:33], v[152:153] neg_lo:[0,1] neg_hi:[0,1]
	v_cmp_neq_f32_e32 vcc, s86, v160
	v_add_f32_e32 v33, v155, v33
	v_add_f32_e32 v32, v32, v33
	v_add_f32_e32 v33, v35, v32
	v_mul_f32_e32 v153, v154, v33
	v_mul_f32_e32 v34, v91, v153
	v_sub_f32_e32 v35, v35, v33
	v_add_f32_e32 v157, v156, v153
	v_fma_f32 v152, v153, v91, -v34
	v_add_f32_e32 v155, v32, v35
	v_sub_f32_e32 v32, v157, v156
	v_fmac_f32_e32 v152, v153, v17
	v_sub_f32_e32 v17, v153, v32
	v_add_f32_e32 v32, v34, v152
	v_sub_f32_e32 v35, v33, v32
	v_mov_b32_e32 v153, v32
	v_pk_add_f32 v[32:33], v[32:33], v[34:35] neg_lo:[0,1] neg_hi:[0,1]
	v_pk_add_f32 v[32:33], v[32:33], v[152:153] neg_lo:[0,1] neg_hi:[0,1]
	v_add_f32_e32 v33, v155, v33
	v_add_f32_e32 v32, v32, v33
	v_add_f32_e32 v32, v35, v32
	v_mul_f32_e32 v32, v154, v32
	v_add_f32_e32 v17, v17, v32
	v_add_f32_e32 v32, v157, v17
	v_mul_f32_e32 v34, v32, v32
	v_sub_f32_e32 v35, v32, v157
	v_fmamk_f32 v91, v34, 0x3e9b6dac, v133
	v_sub_f32_e32 v35, v17, v35
	v_mul_f32_e32 v17, v32, v34
	v_fmaak_f32 v91, v34, v91, 0x3f2aaada
	v_ldexp_f32 v153, v35, 1
	v_pk_mul_f32 v[34:35], v[16:17], v[90:91]
	v_ldexp_f32 v33, v32, 1
	v_fma_f32 v32, v16, s85, -v34
	v_fmac_f32_e32 v32, 0xb102e308, v16
	v_pk_add_f32 v[16:17], v[34:35], v[32:33]
	v_mov_b32_e32 v152, v34
	v_sub_f32_e32 v91, v17, v33
	v_pk_add_f32 v[154:155], v[16:17], v[34:35] neg_lo:[0,1] neg_hi:[0,1]
	v_sub_f32_e32 v34, v35, v91
	v_add_f32_e32 v153, v153, v34
	v_pk_add_f32 v[34:35], v[16:17], v[152:153]
	v_mov_b32_e32 v33, v16
	v_mov_b32_e32 v155, v35
	v_pk_add_f32 v[158:159], v[32:33], v[154:155] neg_lo:[0,1] neg_hi:[0,1]
	v_pk_add_f32 v[32:33], v[32:33], v[154:155]
	v_mov_b32_e32 v157, v16
	v_pk_add_f32 v[154:155], v[32:33], v[16:17] op_sel:[1,0] op_sel_hi:[0,1] neg_lo:[0,1] neg_hi:[0,1]
	v_mov_b32_e32 v156, v153
	v_mov_b32_e32 v152, v35
	v_mov_b32_e32 v153, v33
	v_pk_mov_b32 v[16:17], v[16:17], v[154:155] op_sel:[1,0]
	v_pk_add_f32 v[34:35], v[34:35], v[154:155] op_sel_hi:[1,0] neg_lo:[0,1] neg_hi:[0,1]
	v_pk_add_f32 v[16:17], v[152:153], v[16:17] neg_lo:[0,1] neg_hi:[0,1]
	v_mov_b32_e32 v34, v158
	v_pk_add_f32 v[16:17], v[156:157], v[16:17] neg_lo:[0,1] neg_hi:[0,1]
	v_mov_b32_e32 v159, v33
	v_pk_add_f32 v[34:35], v[34:35], v[16:17]
	v_pk_add_f32 v[152:153], v[34:35], v[34:35] op_sel:[0,1] op_sel_hi:[1,0]
	v_pk_add_f32 v[32:33], v[32:33], v[152:153] op_sel:[1,0] op_sel_hi:[0,1]
	v_mov_b32_e32 v35, v32
	v_mov_b32_e32 v17, v152
	v_pk_add_f32 v[152:153], v[34:35], v[158:159] neg_lo:[0,1] neg_hi:[0,1]
	v_sub_f32_e32 v33, v34, v152
	v_pk_add_f32 v[16:17], v[16:17], v[152:153] neg_lo:[0,1] neg_hi:[0,1]
	v_sub_f32_e32 v33, v158, v33
	v_add_f32_e32 v16, v16, v33
	v_add_f32_e32 v16, v16, v17
	v_add_f32_e32 v16, v32, v16
	v_cndmask_b32_e32 v16, v135, v16, vcc
	v_cmp_ngt_f32_e32 vcc, -1.0, v160
	v_cndmask_b32_e32 v16, v136, v16, vcc
	v_cmp_neq_f32_e32 vcc, -1.0, v160
	v_cndmask_b32_e32 v16, v137, v16, vcc
	v_cmp_lt_f32_e64 vcc, |v160|, s87
	v_cndmask_b32_e32 v16, v16, v160, vcc
	v_mul_f32_e32 v33, 0xc1000000, v16
	ds_write_b32 v138, v33
	v_and_b32_e32 v238, 0x7f, v177
	v_lshrrev_b32_e32 v239, 7, v177
	v_or_b32_e32 v238, s70, v238
	v_lshl_or_b32 v238, v239, 10, v238
	v_lshlrev_b32_e32 v238, 2, v238
	global_load_dword v240, v238, s[26:27]
	v_or_b32_e32 v239, s70, v177
	v_lshlrev_b32_e32 v239, 2, v239
	v_cmp_gt_u32_e32 vcc, 0x80, v177
	s_and_saveexec_b64 s[100:101], vcc
	global_load_dword v241, v239, s[28:29]
	s_mov_b64 exec, s[100:101]
	v_add_u32_e32 v93, 0x200, v92
	v_add_u32_e32 v10, 0x400, v92
	v_add_u32_e32 v12, 0x600, v92
	v_add_u32_e32 v18, 0x800, v92
	v_add_u32_e32 v20, 0xa00, v92
	v_add_u32_e32 v28, 0xc00, v92
	v_add_u32_e32 v30, 0xe00, v92
	v_ashrrev_i32_e32 v9, 4, v92
	s_waitcnt vmcnt(3)
	v_ashrrev_i32_e32 v34, 4, v93
	v_ashrrev_i32_e32 v35, 4, v10
	v_ashrrev_i32_e32 v36, 4, v12
	v_ashrrev_i32_e32 v37, 4, v18
	v_ashrrev_i32_e32 v38, 4, v20
	v_ashrrev_i32_e32 v39, 4, v28
	v_ashrrev_i32_e32 v40, 4, v30
	v_and_b32_e32 v88, 0xf0, v8
	v_lshlrev_b32_e32 v0, 7, v9
	v_lshlrev_b32_e32 v2, 7, v34
	v_lshlrev_b32_e32 v10, 7, v35
	v_lshlrev_b32_e32 v12, 7, v36
	v_lshlrev_b32_e32 v18, 7, v37
	v_lshlrev_b32_e32 v20, 7, v38
	v_lshlrev_b32_e32 v28, 7, v39
	v_lshlrev_b32_e32 v30, 7, v40
	v_lshl_add_u64 v[26:27], s[20:21], 0, v[88:89]
	v_ashrrev_i32_e32 v1, 31, v0
	v_ashrrev_i32_e32 v3, 31, v2
	v_ashrrev_i32_e32 v11, 31, v10
	v_ashrrev_i32_e32 v13, 31, v12
	v_ashrrev_i32_e32 v19, 31, v18
	v_ashrrev_i32_e32 v21, 31, v20
	v_ashrrev_i32_e32 v29, 31, v28
	v_ashrrev_i32_e32 v31, 31, v30
	v_lshl_add_u64 v[0:1], v[0:1], 1, v[26:27]
	v_lshl_add_u64 v[4:5], v[2:3], 1, v[26:27]
	v_lshl_add_u64 v[10:11], v[10:11], 1, v[26:27]
	v_lshl_add_u64 v[14:15], v[12:13], 1, v[26:27]
	v_lshl_add_u64 v[18:19], v[18:19], 1, v[26:27]
	v_lshl_add_u64 v[22:23], v[20:21], 1, v[26:27]
	v_lshl_add_u64 v[28:29], v[28:29], 1, v[26:27]
	v_lshl_add_u64 v[30:31], v[30:31], 1, v[26:27]
	global_load_dwordx4 v[0:3], v[0:1], off
	s_nop 0
	global_load_dwordx4 v[4:7], v[4:5], off
	s_nop 0
	global_load_dwordx4 v[10:13], v[10:11], off
	s_nop 0
	global_load_dwordx4 v[14:17], v[14:15], off
	s_nop 0
	global_load_dwordx4 v[18:21], v[18:19], off
	s_nop 0
	global_load_dwordx4 v[22:25], v[22:23], off
	s_nop 0
	global_load_dwordx4 v[26:29], v[28:29], off
	s_nop 0
	global_load_dwordx4 v[30:33], v[30:31], off
	v_and_b32_e32 v41, 0x70, v92
	v_xad_u32 v41, v88, v41, 16
	v_lshl_add_u32 v9, v9, 8, v41
	v_cmp_gt_i32_e32 vcc, s75, v92
	v_lshl_add_u32 v34, v34, 8, v41
	v_lshl_add_u32 v35, v35, 8, v41
	v_lshl_add_u32 v36, v36, 8, v41
	v_lshl_add_u32 v37, v37, 8, v41
	v_lshl_add_u32 v38, v38, 8, v41
	v_lshl_add_u32 v39, v39, 8, v41
	v_lshl_add_u32 v40, v40, 8, v41
	s_waitcnt vmcnt(7)
	ds_write_b128 v9, v[0:3] offset:16384
	s_waitcnt vmcnt(6)
	ds_write_b128 v34, v[4:7] offset:16384
	s_waitcnt vmcnt(5)
	ds_write_b128 v35, v[10:13] offset:16384
	s_waitcnt vmcnt(4)
	ds_write_b128 v36, v[14:17] offset:16384
	s_waitcnt vmcnt(3)
	ds_write_b128 v37, v[18:21] offset:16384
	s_waitcnt vmcnt(2)
	ds_write_b128 v38, v[22:25] offset:16384
	s_waitcnt vmcnt(1)
	ds_write_b128 v39, v[26:29] offset:16384
	s_waitcnt vmcnt(0)
	ds_write_b128 v40, v[30:33] offset:16384
	v_lshl_add_u32 v238, v177, 2, s78
	ds_write_b32 v238, v240
	v_cmp_gt_u32_e32 vcc, 0x80, v177
	s_and_saveexec_b64 s[100:101], vcc
	ds_write_b32 v238, v241 offset:2048
	s_mov_b64 exec, s[100:101]
.LBB0_319:
.LBB0_320:
	s_and_b32 s63, s57, 63
	s_ashr_i32 s62, s89, 6
	s_lshl_b32 s0, s63, 8
	s_lshl_b32 s1, s62, 5
	v_and_b32_e32 v94, 31, v92
	s_add_i32 s8, s1, s0
	v_or_b32_e32 v9, s8, v94
	v_add_u32_e32 v0, -2, v9
	v_cmp_gt_u32_e32 vcc, s80, v0
	v_bfe_u32 v93, v92, 5, 1
	s_lshl_b32 s14, s70, 1
	v_cndmask_b32_e32 v2, v9, v0, vcc
	v_mov_b64_e32 v[0:1], s[52:53]
	v_mad_i64_i32 v[2:3], s[0:1], v2, s81, v[0:1]
	v_lshl_add_u64 v[2:3], v[2:3], 0, s[14:15]
	v_lshlrev_b32_e32 v88, 4, v93
	v_lshl_add_u64 v[4:5], v[2:3], 0, v[88:89]
	v_add_co_u32_e64 v2, s[0:1], s82, v4
	s_waitcnt lgkmcnt(0)
	s_nop 0
	v_addc_co_u32_e64 v3, s[0:1], 0, v5, s[0:1]
	s_barrier
	global_load_dwordx4 v[10:13], v[2:3], off offset:1024
	global_load_dwordx4 v[178:181], v[2:3], off offset:1056
	global_load_dwordx4 v[194:197], v[2:3], off offset:1088
	global_load_dwordx4 v[210:213], v[2:3], off offset:1120
	global_load_dwordx4 v[226:229], v[2:3], off offset:1152
	global_load_dwordx4 v[242:245], v[2:3], off offset:1184
	v_add_u32_e32 v2, -1, v9
	v_cmp_gt_u32_e64 s[0:1], s80, v2
	v_add_u32_e32 v18, 1, v9
	s_cmpk_lt_u32 s8, 0x4000
	v_cndmask_b32_e64 v2, v9, v2, s[0:1]
	v_mad_i64_i32 v[2:3], s[4:5], v2, s81, v[0:1]
	v_lshl_add_u64 v[2:3], v[2:3], 0, s[14:15]
	v_lshl_add_u64 v[2:3], v[2:3], 0, v[88:89]
	v_add_co_u32_e64 v6, s[4:5], s82, v2
	v_lshlrev_b32_e32 v138, 8, v94
	s_nop 0
	v_addc_co_u32_e64 v7, s[4:5], 0, v3, s[4:5]
	global_load_dwordx4 v[14:17], v[6:7], off offset:1024
	global_load_dwordx4 v[182:185], v[6:7], off offset:1056
	global_load_dwordx4 v[198:201], v[6:7], off offset:1088
	global_load_dwordx4 v[214:217], v[6:7], off offset:1120
	global_load_dwordx4 v[230:233], v[6:7], off offset:1152
	global_load_dwordx4 v[246:249], v[6:7], off offset:1184
	v_mad_i64_i32 v[6:7], s[4:5], v9, s81, v[0:1]
	v_cmp_gt_u32_e64 s[4:5], s80, v18
	v_lshl_add_u64 v[6:7], v[6:7], 0, s[14:15]
	v_lshl_add_u64 v[52:53], v[6:7], 0, v[88:89]
	v_cndmask_b32_e64 v9, v9, v18, s[4:5]
	v_mad_i64_i32 v[0:1], s[6:7], v9, s81, v[0:1]
	v_add_co_u32_e64 v6, s[6:7], s82, v52
	v_lshl_add_u64 v[0:1], v[0:1], 0, s[14:15]
	s_nop 0
	v_addc_co_u32_e64 v7, s[6:7], 0, v53, s[6:7]
	global_load_dwordx4 v[18:21], v[6:7], off offset:1024
	global_load_dwordx4 v[186:189], v[6:7], off offset:1056
	global_load_dwordx4 v[202:205], v[6:7], off offset:1088
	global_load_dwordx4 v[218:221], v[6:7], off offset:1120
	global_load_dwordx4 v[234:237], v[6:7], off offset:1152
	global_load_dwordx4 v[252:255], v[6:7], off offset:1184
	v_lshl_add_u64 v[6:7], v[0:1], 0, v[88:89]
	v_add_co_u32_e64 v0, s[6:7], s82, v6
	v_lshl_add_u32 v9, v93, 5, 16
	s_nop 0
	v_addc_co_u32_e64 v1, s[6:7], 0, v7, s[6:7]
	global_load_dwordx4 v[22:25], v[0:1], off offset:1024
	global_load_dwordx4 v[190:193], v[0:1], off offset:1056
	global_load_dwordx4 v[206:209], v[0:1], off offset:1088
	global_load_dwordx4 v[222:225], v[0:1], off offset:1120
	global_load_dwordx4 v[238:241], v[0:1], off offset:1152
	global_load_dwordx4 v[168:171], v[0:1], off offset:1184
	s_waitcnt vmcnt(26)
	s_waitcnt lgkmcnt(4)
	v_lshl_add_u64 v[0:1], v[4:5], 0, s[30:31]
	s_cselect_b64 s[6:7], -1, 0
	v_lshl_add_u64 v[6:7], v[6:7], 0, s[30:31]
	v_and_b32_e32 v8, 0x70, v8
	v_add_u32_e32 v95, 16, v138
	v_or_b32_e32 v91, s70, v94
	s_waitcnt vmcnt(23)
	s_waitcnt vmcnt(17)
	s_waitcnt lgkmcnt(3)
	s_waitcnt lgkmcnt(1)
	s_waitcnt lgkmcnt(0)
	s_waitcnt vmcnt(11)
	s_waitcnt vmcnt(5)
	ds_read_b128 v[26:29], v9 offset:10240
	ds_read_b128 v[30:33], v9 offset:10256
	ds_read_b128 v[34:37], v9 offset:8192
	ds_read_b128 v[38:41], v9 offset:8208
	ds_read_b128 v[42:45], v9 offset:8704
	ds_read_b128 v[80:83], v9 offset:8720
	s_mov_b64 exec, vcc
	v_lshlrev_b32_e32 v4, 16, v10
	v_and_b32_e32 v5, 0xffff0000, v10
	v_lshlrev_b32_e32 v46, 16, v11
	v_and_b32_e32 v47, 0xffff0000, v11
	s_waitcnt lgkmcnt(2)
	v_pk_fma_f32 v[26:27], v[34:35], v[4:5], v[26:27]
	v_pk_fma_f32 v[28:29], v[36:37], v[46:47], v[28:29]
	v_lshlrev_b32_e32 v84, 16, v12
	v_and_b32_e32 v85, 0xffff0000, v12
	v_lshlrev_b32_e32 v86, 16, v13
	v_and_b32_e32 v87, 0xffff0000, v13
	v_pk_fma_f32 v[30:31], v[38:39], v[84:85], v[30:31]
	v_pk_fma_f32 v[32:33], v[40:41], v[86:87], v[32:33]
	s_mov_b64 exec, -1
	ds_read_b128 v[34:37], v9 offset:9216
	ds_read_b128 v[38:41], v9 offset:9232
	s_mov_b64 exec, s[0:1]
	v_lshlrev_b32_e32 v4, 16, v14
	v_and_b32_e32 v5, 0xffff0000, v14
	v_lshlrev_b32_e32 v46, 16, v15
	v_and_b32_e32 v47, 0xffff0000, v15
	s_waitcnt lgkmcnt(2)
	v_pk_fma_f32 v[26:27], v[42:43], v[4:5], v[26:27]
	v_pk_fma_f32 v[28:29], v[44:45], v[46:47], v[28:29]
	v_lshlrev_b32_e32 v84, 16, v16
	v_and_b32_e32 v85, 0xffff0000, v16
	v_lshlrev_b32_e32 v86, 16, v17
	v_and_b32_e32 v87, 0xffff0000, v17
	v_pk_fma_f32 v[30:31], v[80:81], v[84:85], v[30:31]
	v_pk_fma_f32 v[32:33], v[82:83], v[86:87], v[32:33]
	s_mov_b64 exec, -1
	ds_read_b128 v[42:45], v9 offset:9728
	ds_read_b128 v[80:83], v9 offset:9744
	v_lshlrev_b32_e32 v4, 16, v18
	v_and_b32_e32 v5, 0xffff0000, v18
	v_lshlrev_b32_e32 v46, 16, v19
	v_and_b32_e32 v47, 0xffff0000, v19
	s_waitcnt lgkmcnt(2)
	v_pk_fma_f32 v[26:27], v[34:35], v[4:5], v[26:27]
	v_pk_fma_f32 v[28:29], v[36:37], v[46:47], v[28:29]
	v_lshlrev_b32_e32 v84, 16, v20
	v_and_b32_e32 v85, 0xffff0000, v20
	v_lshlrev_b32_e32 v86, 16, v21
	v_and_b32_e32 v87, 0xffff0000, v21
	v_pk_fma_f32 v[30:31], v[38:39], v[84:85], v[30:31]
	v_pk_fma_f32 v[32:33], v[40:41], v[86:87], v[32:33]
	s_mov_b64 exec, s[4:5]
	v_lshlrev_b32_e32 v4, 16, v22
	v_and_b32_e32 v5, 0xffff0000, v22
	v_lshlrev_b32_e32 v46, 16, v23
	v_and_b32_e32 v47, 0xffff0000, v23
	s_waitcnt lgkmcnt(0)
	v_pk_fma_f32 v[26:27], v[42:43], v[4:5], v[26:27]
	v_pk_fma_f32 v[28:29], v[44:45], v[46:47], v[28:29]
	v_lshlrev_b32_e32 v84, 16, v24
	v_and_b32_e32 v85, 0xffff0000, v24
	v_lshlrev_b32_e32 v86, 16, v25
	v_and_b32_e32 v87, 0xffff0000, v25
	v_pk_fma_f32 v[30:31], v[80:81], v[84:85], v[30:31]
	v_pk_fma_f32 v[32:33], v[82:83], v[86:87], v[32:33]
	s_mov_b64 exec, -1
	v_cvt_pk_bf16_f32 v48, v26, v27
	v_cvt_pk_bf16_f32 v49, v28, v29
	v_cvt_pk_bf16_f32 v50, v30, v31
	v_cvt_pk_bf16_f32 v51, v32, v33
	s_waitcnt lgkmcnt(3)
	s_waitcnt lgkmcnt(1)
	s_waitcnt lgkmcnt(0)
	s_nop 0
	v_lshl_add_u64 v[4:5], v[2:3], 0, s[30:31]
	v_lshl_add_u64 v[2:3], v[52:53], 0, s[30:31]
	s_waitcnt vmcnt(4)
	s_waitcnt vmcnt(4)
	s_waitcnt lgkmcnt(3)
	s_waitcnt lgkmcnt(1)
	s_waitcnt lgkmcnt(0)
	s_waitcnt vmcnt(4)
	ds_read_b128 v[26:29], v9 offset:10304
	ds_read_b128 v[30:33], v9 offset:10320
	ds_read_b128 v[34:37], v9 offset:8256
	ds_read_b128 v[38:41], v9 offset:8272
	ds_read_b128 v[42:45], v9 offset:8768
	ds_read_b128 v[80:83], v9 offset:8784
	s_mov_b64 exec, vcc
	v_lshlrev_b32_e32 v46, 16, v178
	v_and_b32_e32 v47, 0xffff0000, v178
	v_lshlrev_b32_e32 v84, 16, v179
	v_and_b32_e32 v85, 0xffff0000, v179
	s_waitcnt lgkmcnt(2)
	v_pk_fma_f32 v[26:27], v[34:35], v[46:47], v[26:27]
	v_pk_fma_f32 v[28:29], v[36:37], v[84:85], v[28:29]
	v_lshlrev_b32_e32 v86, 16, v180
	v_and_b32_e32 v87, 0xffff0000, v180
	v_lshlrev_b32_e32 v96, 16, v181
	v_and_b32_e32 v97, 0xffff0000, v181
	v_pk_fma_f32 v[30:31], v[38:39], v[86:87], v[30:31]
	v_pk_fma_f32 v[32:33], v[40:41], v[96:97], v[32:33]
	s_mov_b64 exec, -1
	ds_read_b128 v[34:37], v9 offset:9280
	ds_read_b128 v[38:41], v9 offset:9296
	s_mov_b64 exec, s[0:1]
	v_lshlrev_b32_e32 v46, 16, v182
	v_and_b32_e32 v47, 0xffff0000, v182
	v_lshlrev_b32_e32 v84, 16, v183
	v_and_b32_e32 v85, 0xffff0000, v183
	s_waitcnt lgkmcnt(2)
	v_pk_fma_f32 v[26:27], v[42:43], v[46:47], v[26:27]
	v_pk_fma_f32 v[28:29], v[44:45], v[84:85], v[28:29]
	v_lshlrev_b32_e32 v86, 16, v184
	v_and_b32_e32 v87, 0xffff0000, v184
	v_lshlrev_b32_e32 v96, 16, v185
	v_and_b32_e32 v97, 0xffff0000, v185
	v_pk_fma_f32 v[30:31], v[80:81], v[86:87], v[30:31]
	v_pk_fma_f32 v[32:33], v[82:83], v[96:97], v[32:33]
	s_mov_b64 exec, -1
	ds_read_b128 v[42:45], v9 offset:9792
	ds_read_b128 v[80:83], v9 offset:9808
	v_lshlrev_b32_e32 v46, 16, v186
	v_and_b32_e32 v47, 0xffff0000, v186
	v_lshlrev_b32_e32 v84, 16, v187
	v_and_b32_e32 v85, 0xffff0000, v187
	s_waitcnt lgkmcnt(2)
	v_pk_fma_f32 v[26:27], v[34:35], v[46:47], v[26:27]
	v_pk_fma_f32 v[28:29], v[36:37], v[84:85], v[28:29]
	v_lshlrev_b32_e32 v86, 16, v188
	v_and_b32_e32 v87, 0xffff0000, v188
	v_lshlrev_b32_e32 v96, 16, v189
	v_and_b32_e32 v97, 0xffff0000, v189
	v_pk_fma_f32 v[30:31], v[38:39], v[86:87], v[30:31]
	v_pk_fma_f32 v[32:33], v[40:41], v[96:97], v[32:33]
	s_mov_b64 exec, s[4:5]
	v_lshlrev_b32_e32 v46, 16, v190
	v_and_b32_e32 v47, 0xffff0000, v190
	v_lshlrev_b32_e32 v84, 16, v191
	v_and_b32_e32 v85, 0xffff0000, v191
	s_waitcnt lgkmcnt(0)
	v_pk_fma_f32 v[26:27], v[42:43], v[46:47], v[26:27]
	v_pk_fma_f32 v[28:29], v[44:45], v[84:85], v[28:29]
	v_lshlrev_b32_e32 v86, 16, v192
	v_and_b32_e32 v87, 0xffff0000, v192
	v_lshlrev_b32_e32 v96, 16, v193
	v_and_b32_e32 v97, 0xffff0000, v193
	v_pk_fma_f32 v[30:31], v[80:81], v[86:87], v[30:31]
	v_pk_fma_f32 v[32:33], v[82:83], v[96:97], v[32:33]
	s_mov_b64 exec, -1
	v_cvt_pk_bf16_f32 v52, v26, v27
	v_cvt_pk_bf16_f32 v53, v28, v29
	v_cvt_pk_bf16_f32 v54, v30, v31
	v_cvt_pk_bf16_f32 v55, v32, v33
	s_waitcnt lgkmcnt(3)
	s_waitcnt lgkmcnt(1)
	s_waitcnt lgkmcnt(0)
	s_nop 0
	global_load_dwordx4 v[178:181], v[0:1], off offset:192
	global_load_dwordx4 v[182:185], v[4:5], off offset:192
	global_load_dwordx4 v[186:189], v[2:3], off offset:192
	global_load_dwordx4 v[190:193], v[6:7], off offset:192
	s_waitcnt vmcnt(7)
	s_waitcnt vmcnt(7)
	s_waitcnt lgkmcnt(3)
	s_waitcnt lgkmcnt(1)
	s_waitcnt lgkmcnt(0)
	s_waitcnt vmcnt(7)
	s_waitcnt vmcnt(7)
	ds_read_b128 v[26:29], v9 offset:10368
	ds_read_b128 v[30:33], v9 offset:10384
	ds_read_b128 v[34:37], v9 offset:8320
	ds_read_b128 v[38:41], v9 offset:8336
	ds_read_b128 v[42:45], v9 offset:8832
	ds_read_b128 v[80:83], v9 offset:8848
	s_mov_b64 exec, vcc
	v_lshlrev_b32_e32 v46, 16, v194
	v_and_b32_e32 v47, 0xffff0000, v194
	v_lshlrev_b32_e32 v84, 16, v195
	v_and_b32_e32 v85, 0xffff0000, v195
	s_waitcnt lgkmcnt(2)
	v_pk_fma_f32 v[26:27], v[34:35], v[46:47], v[26:27]
	v_pk_fma_f32 v[28:29], v[36:37], v[84:85], v[28:29]
	v_lshlrev_b32_e32 v86, 16, v196
	v_and_b32_e32 v87, 0xffff0000, v196
	v_lshlrev_b32_e32 v96, 16, v197
	v_and_b32_e32 v97, 0xffff0000, v197
	v_pk_fma_f32 v[30:31], v[38:39], v[86:87], v[30:31]
	v_pk_fma_f32 v[32:33], v[40:41], v[96:97], v[32:33]
	s_mov_b64 exec, -1
	ds_read_b128 v[34:37], v9 offset:9344
	ds_read_b128 v[38:41], v9 offset:9360
	s_mov_b64 exec, s[0:1]
	v_lshlrev_b32_e32 v46, 16, v198
	v_and_b32_e32 v47, 0xffff0000, v198
	v_lshlrev_b32_e32 v84, 16, v199
	v_and_b32_e32 v85, 0xffff0000, v199
	s_waitcnt lgkmcnt(2)
	v_pk_fma_f32 v[26:27], v[42:43], v[46:47], v[26:27]
	v_pk_fma_f32 v[28:29], v[44:45], v[84:85], v[28:29]
	v_lshlrev_b32_e32 v86, 16, v200
	v_and_b32_e32 v87, 0xffff0000, v200
	v_lshlrev_b32_e32 v96, 16, v201
	v_and_b32_e32 v97, 0xffff0000, v201
	v_pk_fma_f32 v[30:31], v[80:81], v[86:87], v[30:31]
	v_pk_fma_f32 v[32:33], v[82:83], v[96:97], v[32:33]
	s_mov_b64 exec, -1
	ds_read_b128 v[42:45], v9 offset:9856
	ds_read_b128 v[80:83], v9 offset:9872
	v_lshlrev_b32_e32 v46, 16, v202
	v_and_b32_e32 v47, 0xffff0000, v202
	v_lshlrev_b32_e32 v84, 16, v203
	v_and_b32_e32 v85, 0xffff0000, v203
	s_waitcnt lgkmcnt(2)
	v_pk_fma_f32 v[26:27], v[34:35], v[46:47], v[26:27]
	v_pk_fma_f32 v[28:29], v[36:37], v[84:85], v[28:29]
	v_lshlrev_b32_e32 v86, 16, v204
	v_and_b32_e32 v87, 0xffff0000, v204
	v_lshlrev_b32_e32 v96, 16, v205
	v_and_b32_e32 v97, 0xffff0000, v205
	v_pk_fma_f32 v[30:31], v[38:39], v[86:87], v[30:31]
	v_pk_fma_f32 v[32:33], v[40:41], v[96:97], v[32:33]
	s_mov_b64 exec, s[4:5]
	v_lshlrev_b32_e32 v46, 16, v206
	v_and_b32_e32 v47, 0xffff0000, v206
	v_lshlrev_b32_e32 v84, 16, v207
	v_and_b32_e32 v85, 0xffff0000, v207
	s_waitcnt lgkmcnt(0)
	v_pk_fma_f32 v[26:27], v[42:43], v[46:47], v[26:27]
	v_pk_fma_f32 v[28:29], v[44:45], v[84:85], v[28:29]
	v_lshlrev_b32_e32 v86, 16, v208
	v_and_b32_e32 v87, 0xffff0000, v208
	v_lshlrev_b32_e32 v96, 16, v209
	v_and_b32_e32 v97, 0xffff0000, v209
	v_pk_fma_f32 v[30:31], v[80:81], v[86:87], v[30:31]
	v_pk_fma_f32 v[32:33], v[82:83], v[96:97], v[32:33]
	s_mov_b64 exec, -1
	v_cvt_pk_bf16_f32 v56, v26, v27
	v_cvt_pk_bf16_f32 v57, v28, v29
	v_cvt_pk_bf16_f32 v58, v30, v31
	v_cvt_pk_bf16_f32 v59, v32, v33
	s_waitcnt lgkmcnt(3)
	s_waitcnt lgkmcnt(1)
	s_waitcnt lgkmcnt(0)
	s_nop 0
	global_load_dwordx4 v[194:197], v[0:1], off offset:224
	global_load_dwordx4 v[198:201], v[4:5], off offset:224
	global_load_dwordx4 v[202:205], v[2:3], off offset:224
	global_load_dwordx4 v[206:209], v[6:7], off offset:224
	s_waitcnt vmcnt(10)
	s_waitcnt vmcnt(10)
	s_waitcnt lgkmcnt(3)
	s_waitcnt lgkmcnt(1)
	s_waitcnt lgkmcnt(0)
	s_waitcnt vmcnt(10)
	s_waitcnt vmcnt(10)
	ds_read_b128 v[0:3], v9 offset:10432
	ds_read_b128 v[4:7], v9 offset:10448
	ds_read_b128 v[26:29], v9 offset:8384
	ds_read_b128 v[30:33], v9 offset:8400
	ds_read_b128 v[34:37], v9 offset:8896
	ds_read_b128 v[38:41], v9 offset:8912
	s_mov_b64 exec, vcc
	v_lshlrev_b32_e32 v42, 16, v210
	v_and_b32_e32 v43, 0xffff0000, v210
	v_lshlrev_b32_e32 v44, 16, v211
	v_and_b32_e32 v45, 0xffff0000, v211
	s_waitcnt lgkmcnt(2)
	v_pk_fma_f32 v[0:1], v[26:27], v[42:43], v[0:1]
	v_pk_fma_f32 v[2:3], v[28:29], v[44:45], v[2:3]
	v_lshlrev_b32_e32 v46, 16, v212
	v_and_b32_e32 v47, 0xffff0000, v212
	v_lshlrev_b32_e32 v80, 16, v213
	v_and_b32_e32 v81, 0xffff0000, v213
	v_pk_fma_f32 v[4:5], v[30:31], v[46:47], v[4:5]
	v_pk_fma_f32 v[6:7], v[32:33], v[80:81], v[6:7]
	s_mov_b64 exec, -1
	ds_read_b128 v[26:29], v9 offset:9408
	ds_read_b128 v[30:33], v9 offset:9424
	s_mov_b64 exec, s[0:1]
	v_lshlrev_b32_e32 v42, 16, v214
	v_and_b32_e32 v43, 0xffff0000, v214
	v_lshlrev_b32_e32 v44, 16, v215
	v_and_b32_e32 v45, 0xffff0000, v215
	s_waitcnt lgkmcnt(2)
	v_pk_fma_f32 v[0:1], v[34:35], v[42:43], v[0:1]
	v_pk_fma_f32 v[2:3], v[36:37], v[44:45], v[2:3]
	v_lshlrev_b32_e32 v46, 16, v216
	v_and_b32_e32 v47, 0xffff0000, v216
	v_lshlrev_b32_e32 v80, 16, v217
	v_and_b32_e32 v81, 0xffff0000, v217
	v_pk_fma_f32 v[4:5], v[38:39], v[46:47], v[4:5]
	v_pk_fma_f32 v[6:7], v[40:41], v[80:81], v[6:7]
	s_mov_b64 exec, -1
	ds_read_b128 v[34:37], v9 offset:9920
	ds_read_b128 v[38:41], v9 offset:9936
	v_lshlrev_b32_e32 v42, 16, v218
	v_and_b32_e32 v43, 0xffff0000, v218
	v_lshlrev_b32_e32 v44, 16, v219
	v_and_b32_e32 v45, 0xffff0000, v219
	s_waitcnt lgkmcnt(2)
	v_pk_fma_f32 v[0:1], v[26:27], v[42:43], v[0:1]
	v_pk_fma_f32 v[2:3], v[28:29], v[44:45], v[2:3]
	v_lshlrev_b32_e32 v46, 16, v220
	v_and_b32_e32 v47, 0xffff0000, v220
	v_lshlrev_b32_e32 v80, 16, v221
	v_and_b32_e32 v81, 0xffff0000, v221
	v_pk_fma_f32 v[4:5], v[30:31], v[46:47], v[4:5]
	v_pk_fma_f32 v[6:7], v[32:33], v[80:81], v[6:7]
	s_mov_b64 exec, s[4:5]
	v_lshlrev_b32_e32 v42, 16, v222
	v_and_b32_e32 v43, 0xffff0000, v222
	v_lshlrev_b32_e32 v44, 16, v223
	v_and_b32_e32 v45, 0xffff0000, v223
	s_waitcnt lgkmcnt(0)
	v_pk_fma_f32 v[0:1], v[34:35], v[42:43], v[0:1]
	v_pk_fma_f32 v[2:3], v[36:37], v[44:45], v[2:3]
	v_lshlrev_b32_e32 v46, 16, v224
	v_and_b32_e32 v47, 0xffff0000, v224
	v_lshlrev_b32_e32 v80, 16, v225
	v_and_b32_e32 v81, 0xffff0000, v225
	v_pk_fma_f32 v[4:5], v[38:39], v[46:47], v[4:5]
	v_pk_fma_f32 v[6:7], v[40:41], v[80:81], v[6:7]
	s_mov_b64 exec, -1
	v_cvt_pk_bf16_f32 v60, v0, v1
	v_cvt_pk_bf16_f32 v61, v2, v3
	v_cvt_pk_bf16_f32 v62, v4, v5
	v_cvt_pk_bf16_f32 v63, v6, v7
	s_waitcnt lgkmcnt(3)
	s_waitcnt lgkmcnt(1)
	s_waitcnt lgkmcnt(0)
	s_nop 0
	s_waitcnt vmcnt(9)
	s_waitcnt vmcnt(9)
	s_waitcnt lgkmcnt(3)
	s_waitcnt lgkmcnt(1)
	s_waitcnt lgkmcnt(0)
	s_waitcnt vmcnt(9)
	s_waitcnt vmcnt(9)
	ds_read_b128 v[0:3], v9 offset:10496
	ds_read_b128 v[4:7], v9 offset:10512
	ds_read_b128 v[26:29], v9 offset:8448
	ds_read_b128 v[30:33], v9 offset:8464
	ds_read_b128 v[34:37], v9 offset:8960
	ds_read_b128 v[38:41], v9 offset:8976
	s_mov_b64 exec, vcc
	v_lshlrev_b32_e32 v42, 16, v226
	v_and_b32_e32 v43, 0xffff0000, v226
	v_lshlrev_b32_e32 v44, 16, v227
	v_and_b32_e32 v45, 0xffff0000, v227
	s_waitcnt lgkmcnt(2)
	v_pk_fma_f32 v[0:1], v[26:27], v[42:43], v[0:1]
	v_pk_fma_f32 v[2:3], v[28:29], v[44:45], v[2:3]
	v_lshlrev_b32_e32 v46, 16, v228
	v_and_b32_e32 v47, 0xffff0000, v228
	v_lshlrev_b32_e32 v80, 16, v229
	v_and_b32_e32 v81, 0xffff0000, v229
	v_pk_fma_f32 v[4:5], v[30:31], v[46:47], v[4:5]
	v_pk_fma_f32 v[6:7], v[32:33], v[80:81], v[6:7]
	s_mov_b64 exec, -1
	ds_read_b128 v[26:29], v9 offset:9472
	ds_read_b128 v[30:33], v9 offset:9488
	s_mov_b64 exec, s[0:1]
	v_lshlrev_b32_e32 v42, 16, v230
	v_and_b32_e32 v43, 0xffff0000, v230
	v_lshlrev_b32_e32 v44, 16, v231
	v_and_b32_e32 v45, 0xffff0000, v231
	s_waitcnt lgkmcnt(2)
	v_pk_fma_f32 v[0:1], v[34:35], v[42:43], v[0:1]
	v_pk_fma_f32 v[2:3], v[36:37], v[44:45], v[2:3]
	v_lshlrev_b32_e32 v46, 16, v232
	v_and_b32_e32 v47, 0xffff0000, v232
	v_lshlrev_b32_e32 v80, 16, v233
	v_and_b32_e32 v81, 0xffff0000, v233
	v_pk_fma_f32 v[4:5], v[38:39], v[46:47], v[4:5]
	v_pk_fma_f32 v[6:7], v[40:41], v[80:81], v[6:7]
	s_mov_b64 exec, -1
	ds_read_b128 v[34:37], v9 offset:9984
	ds_read_b128 v[38:41], v9 offset:10000
	v_lshlrev_b32_e32 v42, 16, v234
	v_and_b32_e32 v43, 0xffff0000, v234
	v_lshlrev_b32_e32 v44, 16, v235
	v_and_b32_e32 v45, 0xffff0000, v235
	s_waitcnt lgkmcnt(2)
	v_pk_fma_f32 v[0:1], v[26:27], v[42:43], v[0:1]
	v_pk_fma_f32 v[2:3], v[28:29], v[44:45], v[2:3]
	v_lshlrev_b32_e32 v46, 16, v236
	v_and_b32_e32 v47, 0xffff0000, v236
	v_lshlrev_b32_e32 v80, 16, v237
	v_and_b32_e32 v81, 0xffff0000, v237
	v_pk_fma_f32 v[4:5], v[30:31], v[46:47], v[4:5]
	v_pk_fma_f32 v[6:7], v[32:33], v[80:81], v[6:7]
	s_mov_b64 exec, s[4:5]
	v_lshlrev_b32_e32 v42, 16, v238
	v_and_b32_e32 v43, 0xffff0000, v238
	v_lshlrev_b32_e32 v44, 16, v239
	v_and_b32_e32 v45, 0xffff0000, v239
	s_waitcnt lgkmcnt(0)
	v_pk_fma_f32 v[0:1], v[34:35], v[42:43], v[0:1]
	v_pk_fma_f32 v[2:3], v[36:37], v[44:45], v[2:3]
	v_lshlrev_b32_e32 v46, 16, v240
	v_and_b32_e32 v47, 0xffff0000, v240
	v_lshlrev_b32_e32 v80, 16, v241
	v_and_b32_e32 v81, 0xffff0000, v241
	v_pk_fma_f32 v[4:5], v[38:39], v[46:47], v[4:5]
	v_pk_fma_f32 v[6:7], v[40:41], v[80:81], v[6:7]
	s_mov_b64 exec, -1
	v_cvt_pk_bf16_f32 v64, v0, v1
	v_cvt_pk_bf16_f32 v65, v2, v3
	v_cvt_pk_bf16_f32 v66, v4, v5
	v_cvt_pk_bf16_f32 v67, v6, v7
	s_waitcnt lgkmcnt(3)
	s_waitcnt lgkmcnt(1)
	s_waitcnt lgkmcnt(0)
	s_nop 0
	s_waitcnt vmcnt(8)
	s_waitcnt vmcnt(8)
	s_waitcnt lgkmcnt(3)
	s_waitcnt lgkmcnt(1)
	s_waitcnt lgkmcnt(0)
	s_waitcnt vmcnt(8)
	s_waitcnt vmcnt(8)
	ds_read_b128 v[0:3], v9 offset:10560
	ds_read_b128 v[4:7], v9 offset:10576
	ds_read_b128 v[26:29], v9 offset:8512
	ds_read_b128 v[30:33], v9 offset:8528
	ds_read_b128 v[34:37], v9 offset:9024
	ds_read_b128 v[38:41], v9 offset:9040
	s_mov_b64 exec, vcc
	v_lshlrev_b32_e32 v42, 16, v242
	v_and_b32_e32 v43, 0xffff0000, v242
	v_lshlrev_b32_e32 v44, 16, v243
	v_and_b32_e32 v45, 0xffff0000, v243
	s_waitcnt lgkmcnt(2)
	v_pk_fma_f32 v[0:1], v[26:27], v[42:43], v[0:1]
	v_pk_fma_f32 v[2:3], v[28:29], v[44:45], v[2:3]
	v_lshlrev_b32_e32 v46, 16, v244
	v_and_b32_e32 v47, 0xffff0000, v244
	v_lshlrev_b32_e32 v80, 16, v245
	v_and_b32_e32 v81, 0xffff0000, v245
	v_pk_fma_f32 v[4:5], v[30:31], v[46:47], v[4:5]
	v_pk_fma_f32 v[6:7], v[32:33], v[80:81], v[6:7]
	s_mov_b64 exec, -1
	ds_read_b128 v[26:29], v9 offset:9536
	ds_read_b128 v[30:33], v9 offset:9552
	s_mov_b64 exec, s[0:1]
	v_lshlrev_b32_e32 v42, 16, v246
	v_and_b32_e32 v43, 0xffff0000, v246
	v_lshlrev_b32_e32 v44, 16, v247
	v_and_b32_e32 v45, 0xffff0000, v247
	s_waitcnt lgkmcnt(2)
	v_pk_fma_f32 v[0:1], v[34:35], v[42:43], v[0:1]
	v_pk_fma_f32 v[2:3], v[36:37], v[44:45], v[2:3]
	v_lshlrev_b32_e32 v46, 16, v248
	v_and_b32_e32 v47, 0xffff0000, v248
	v_lshlrev_b32_e32 v80, 16, v249
	v_and_b32_e32 v81, 0xffff0000, v249
	v_pk_fma_f32 v[4:5], v[38:39], v[46:47], v[4:5]
	v_pk_fma_f32 v[6:7], v[40:41], v[80:81], v[6:7]
	s_mov_b64 exec, -1
	ds_read_b128 v[34:37], v9 offset:10048
	ds_read_b128 v[38:41], v9 offset:10064
	v_lshlrev_b32_e32 v42, 16, v252
	v_and_b32_e32 v43, 0xffff0000, v252
	v_lshlrev_b32_e32 v44, 16, v253
	v_and_b32_e32 v45, 0xffff0000, v253
	s_waitcnt lgkmcnt(2)
	v_pk_fma_f32 v[0:1], v[26:27], v[42:43], v[0:1]
	v_pk_fma_f32 v[2:3], v[28:29], v[44:45], v[2:3]
	v_lshlrev_b32_e32 v46, 16, v254
	v_and_b32_e32 v47, 0xffff0000, v254
	v_lshlrev_b32_e32 v80, 16, v255
	v_and_b32_e32 v81, 0xffff0000, v255
	v_pk_fma_f32 v[4:5], v[30:31], v[46:47], v[4:5]
	v_pk_fma_f32 v[6:7], v[32:33], v[80:81], v[6:7]
	s_mov_b64 exec, s[4:5]
	v_lshlrev_b32_e32 v42, 16, v168
	v_and_b32_e32 v43, 0xffff0000, v168
	v_lshlrev_b32_e32 v44, 16, v169
	v_and_b32_e32 v45, 0xffff0000, v169
	s_waitcnt lgkmcnt(0)
	v_pk_fma_f32 v[0:1], v[34:35], v[42:43], v[0:1]
	v_pk_fma_f32 v[2:3], v[36:37], v[44:45], v[2:3]
	v_lshlrev_b32_e32 v46, 16, v170
	v_and_b32_e32 v47, 0xffff0000, v170
	v_lshlrev_b32_e32 v80, 16, v171
	v_and_b32_e32 v81, 0xffff0000, v171
	v_pk_fma_f32 v[4:5], v[38:39], v[46:47], v[4:5]
	v_pk_fma_f32 v[6:7], v[40:41], v[80:81], v[6:7]
	s_mov_b64 exec, -1
	v_cvt_pk_bf16_f32 v68, v0, v1
	v_cvt_pk_bf16_f32 v69, v2, v3
	v_cvt_pk_bf16_f32 v70, v4, v5
	v_cvt_pk_bf16_f32 v71, v6, v7
	s_waitcnt lgkmcnt(3)
	s_waitcnt lgkmcnt(1)
	s_waitcnt lgkmcnt(0)
	s_nop 0
	s_waitcnt vmcnt(4)
	s_waitcnt vmcnt(4)
	s_waitcnt lgkmcnt(3)
	s_waitcnt lgkmcnt(1)
	s_waitcnt lgkmcnt(0)
	s_waitcnt vmcnt(4)
	s_waitcnt vmcnt(4)
	ds_read_b128 v[0:3], v9 offset:10624
	ds_read_b128 v[4:7], v9 offset:10640
	ds_read_b128 v[26:29], v9 offset:8576
	ds_read_b128 v[30:33], v9 offset:8592
	ds_read_b128 v[34:37], v9 offset:9088
	ds_read_b128 v[38:41], v9 offset:9104
	s_mov_b64 exec, vcc
	v_lshlrev_b32_e32 v42, 16, v178
	v_and_b32_e32 v43, 0xffff0000, v178
	v_lshlrev_b32_e32 v44, 16, v179
	v_and_b32_e32 v45, 0xffff0000, v179
	s_waitcnt lgkmcnt(2)
	v_pk_fma_f32 v[0:1], v[26:27], v[42:43], v[0:1]
	v_pk_fma_f32 v[2:3], v[28:29], v[44:45], v[2:3]
	v_lshlrev_b32_e32 v46, 16, v180
	v_and_b32_e32 v47, 0xffff0000, v180
	v_lshlrev_b32_e32 v80, 16, v181
	v_and_b32_e32 v81, 0xffff0000, v181
	v_pk_fma_f32 v[4:5], v[30:31], v[46:47], v[4:5]
	v_pk_fma_f32 v[6:7], v[32:33], v[80:81], v[6:7]
	s_mov_b64 exec, -1
	ds_read_b128 v[26:29], v9 offset:9600
	ds_read_b128 v[30:33], v9 offset:9616
	s_mov_b64 exec, s[0:1]
	v_lshlrev_b32_e32 v42, 16, v182
	v_and_b32_e32 v43, 0xffff0000, v182
	v_lshlrev_b32_e32 v44, 16, v183
	v_and_b32_e32 v45, 0xffff0000, v183
	s_waitcnt lgkmcnt(2)
	v_pk_fma_f32 v[0:1], v[34:35], v[42:43], v[0:1]
	v_pk_fma_f32 v[2:3], v[36:37], v[44:45], v[2:3]
	v_lshlrev_b32_e32 v46, 16, v184
	v_and_b32_e32 v47, 0xffff0000, v184
	v_lshlrev_b32_e32 v80, 16, v185
	v_and_b32_e32 v81, 0xffff0000, v185
	v_pk_fma_f32 v[4:5], v[38:39], v[46:47], v[4:5]
	v_pk_fma_f32 v[6:7], v[40:41], v[80:81], v[6:7]
	s_mov_b64 exec, -1
	ds_read_b128 v[34:37], v9 offset:10112
	ds_read_b128 v[38:41], v9 offset:10128
	v_lshlrev_b32_e32 v42, 16, v186
	v_and_b32_e32 v43, 0xffff0000, v186
	v_lshlrev_b32_e32 v44, 16, v187
	v_and_b32_e32 v45, 0xffff0000, v187
	s_waitcnt lgkmcnt(2)
	v_pk_fma_f32 v[0:1], v[26:27], v[42:43], v[0:1]
	v_pk_fma_f32 v[2:3], v[28:29], v[44:45], v[2:3]
	v_lshlrev_b32_e32 v46, 16, v188
	v_and_b32_e32 v47, 0xffff0000, v188
	v_lshlrev_b32_e32 v80, 16, v189
	v_and_b32_e32 v81, 0xffff0000, v189
	v_pk_fma_f32 v[4:5], v[30:31], v[46:47], v[4:5]
	v_pk_fma_f32 v[6:7], v[32:33], v[80:81], v[6:7]
	s_mov_b64 exec, s[4:5]
	v_lshlrev_b32_e32 v42, 16, v190
	v_and_b32_e32 v43, 0xffff0000, v190
	v_lshlrev_b32_e32 v44, 16, v191
	v_and_b32_e32 v45, 0xffff0000, v191
	s_waitcnt lgkmcnt(0)
	v_pk_fma_f32 v[0:1], v[34:35], v[42:43], v[0:1]
	v_pk_fma_f32 v[2:3], v[36:37], v[44:45], v[2:3]
	v_lshlrev_b32_e32 v46, 16, v192
	v_and_b32_e32 v47, 0xffff0000, v192
	v_lshlrev_b32_e32 v80, 16, v193
	v_and_b32_e32 v81, 0xffff0000, v193
	v_pk_fma_f32 v[4:5], v[38:39], v[46:47], v[4:5]
	v_pk_fma_f32 v[6:7], v[40:41], v[80:81], v[6:7]
	s_mov_b64 exec, -1
	v_cvt_pk_bf16_f32 v72, v0, v1
	v_cvt_pk_bf16_f32 v73, v2, v3
	v_cvt_pk_bf16_f32 v74, v4, v5
	v_cvt_pk_bf16_f32 v75, v6, v7
	s_waitcnt lgkmcnt(3)
	s_waitcnt lgkmcnt(1)
	s_waitcnt lgkmcnt(0)
	v_lshlrev_b32_e32 v38, 3, v93
	s_nop 0
	s_nop 0
	v_or_b32_e32 v39, 16, v38
	s_waitcnt vmcnt(0)
	s_waitcnt vmcnt(0)
	s_waitcnt lgkmcnt(3)
	s_waitcnt lgkmcnt(1)
	s_waitcnt lgkmcnt(0)
	s_waitcnt vmcnt(0)
	s_waitcnt vmcnt(0)
	ds_read_b128 v[0:3], v9 offset:10688
	ds_read_b128 v[4:7], v9 offset:10704
	ds_read_b128 v[26:29], v9 offset:8640
	ds_read_b128 v[30:33], v9 offset:8656
	ds_read_b128 v[34:37], v9 offset:9152
	ds_read_b128 v[40:43], v9 offset:9168
	s_mov_b64 exec, vcc
	v_lshlrev_b32_e32 v44, 16, v194
	v_and_b32_e32 v45, 0xffff0000, v194
	v_lshlrev_b32_e32 v46, 16, v195
	v_and_b32_e32 v47, 0xffff0000, v195
	s_waitcnt lgkmcnt(2)
	v_pk_fma_f32 v[0:1], v[26:27], v[44:45], v[0:1]
	v_pk_fma_f32 v[2:3], v[28:29], v[46:47], v[2:3]
	v_lshlrev_b32_e32 v80, 16, v196
	v_and_b32_e32 v81, 0xffff0000, v196
	v_lshlrev_b32_e32 v82, 16, v197
	v_and_b32_e32 v83, 0xffff0000, v197
	v_pk_fma_f32 v[4:5], v[30:31], v[80:81], v[4:5]
	v_pk_fma_f32 v[6:7], v[32:33], v[82:83], v[6:7]
	s_mov_b64 exec, -1
	ds_read_b128 v[26:29], v9 offset:9664
	ds_read_b128 v[30:33], v9 offset:9680
	s_mov_b64 exec, s[0:1]
	v_lshlrev_b32_e32 v44, 16, v198
	v_and_b32_e32 v45, 0xffff0000, v198
	v_lshlrev_b32_e32 v46, 16, v199
	v_and_b32_e32 v47, 0xffff0000, v199
	s_waitcnt lgkmcnt(2)
	v_pk_fma_f32 v[0:1], v[34:35], v[44:45], v[0:1]
	v_pk_fma_f32 v[2:3], v[36:37], v[46:47], v[2:3]
	v_lshlrev_b32_e32 v80, 16, v200
	v_and_b32_e32 v81, 0xffff0000, v200
	v_lshlrev_b32_e32 v82, 16, v201
	v_and_b32_e32 v83, 0xffff0000, v201
	v_pk_fma_f32 v[4:5], v[40:41], v[80:81], v[4:5]
	v_pk_fma_f32 v[6:7], v[42:43], v[82:83], v[6:7]
	s_mov_b64 exec, -1
	ds_read_b128 v[34:37], v9 offset:10176
	ds_read_b128 v[40:43], v9 offset:10192
	v_lshlrev_b32_e32 v44, 16, v202
	v_and_b32_e32 v45, 0xffff0000, v202
	v_lshlrev_b32_e32 v46, 16, v203
	v_and_b32_e32 v47, 0xffff0000, v203
	s_waitcnt lgkmcnt(2)
	v_pk_fma_f32 v[0:1], v[26:27], v[44:45], v[0:1]
	v_pk_fma_f32 v[2:3], v[28:29], v[46:47], v[2:3]
	v_lshlrev_b32_e32 v80, 16, v204
	v_and_b32_e32 v81, 0xffff0000, v204
	v_lshlrev_b32_e32 v82, 16, v205
	v_and_b32_e32 v83, 0xffff0000, v205
	v_pk_fma_f32 v[4:5], v[30:31], v[80:81], v[4:5]
	v_pk_fma_f32 v[6:7], v[32:33], v[82:83], v[6:7]
	s_mov_b64 exec, s[4:5]
	v_lshlrev_b32_e32 v44, 16, v206
	v_and_b32_e32 v45, 0xffff0000, v206
	v_lshlrev_b32_e32 v46, 16, v207
	v_and_b32_e32 v47, 0xffff0000, v207
	s_waitcnt lgkmcnt(0)
	v_pk_fma_f32 v[0:1], v[34:35], v[44:45], v[0:1]
	v_pk_fma_f32 v[2:3], v[36:37], v[46:47], v[2:3]
	v_lshlrev_b32_e32 v80, 16, v208
	v_and_b32_e32 v81, 0xffff0000, v208
	v_lshlrev_b32_e32 v82, 16, v209
	v_and_b32_e32 v83, 0xffff0000, v209
	v_pk_fma_f32 v[4:5], v[40:41], v[80:81], v[4:5]
	v_pk_fma_f32 v[6:7], v[42:43], v[82:83], v[6:7]
	s_mov_b64 exec, -1
	v_cvt_pk_bf16_f32 v76, v0, v1
	v_cvt_pk_bf16_f32 v77, v2, v3
	v_cvt_pk_bf16_f32 v78, v4, v5
	v_cvt_pk_bf16_f32 v79, v6, v7
	s_waitcnt lgkmcnt(3)
	s_waitcnt lgkmcnt(1)
	s_waitcnt lgkmcnt(0)
	v_cmp_eq_u32_e32 vcc, v38, v94
	v_or_b32_e32 v2, 1, v38
	v_cndmask_b32_e32 v0, 0, v134, vcc
	v_or_b32_e32 v1, 2, v38
	v_cmp_eq_u32_e32 vcc, v2, v94
	v_or_b32_e32 v4, 3, v38
	v_or_b32_e32 v3, 4, v38
	v_cndmask_b32_e32 v2, 0, v134, vcc
	v_cmp_eq_u32_e32 vcc, v1, v94
	v_or_b32_e32 v5, 6, v38
	v_or_b32_e32 v6, 5, v38
	v_cndmask_b32_e32 v1, 0, v134, vcc
	v_cmp_eq_u32_e32 vcc, v4, v94
	v_or_b32_e32 v7, 7, v38
	v_or_b32_e32 v11, 17, v38
	v_cndmask_b32_e32 v4, 0, v134, vcc
	v_cmp_eq_u32_e32 vcc, v3, v94
	v_or_b32_e32 v10, 18, v38
	v_or_b32_e32 v13, 19, v38
	v_cndmask_b32_e32 v3, 0, v134, vcc
	v_cmp_eq_u32_e32 vcc, v5, v94
	v_or_b32_e32 v12, 20, v38
	v_or_b32_e32 v14, 22, v38
	v_cndmask_b32_e32 v5, 0, v134, vcc
	v_cmp_eq_u32_e32 vcc, v6, v94
	v_or_b32_e32 v15, 21, v38
	v_or_b32_e32 v16, 23, v38
	v_cndmask_b32_e32 v6, 0, v134, vcc
	v_cmp_eq_u32_e32 vcc, v7, v94
	v_and_b32_e32 v18, 64, v132
	v_xor_b32_e32 v17, 32, v132
	v_cndmask_b32_e32 v7, 0, v134, vcc
	v_cmp_eq_u32_e32 vcc, v39, v94
	v_add_u32_e32 v18, 64, v18
	s_lshl_b32 s4, s62, 8
	v_cndmask_b32_e32 v9, 0, v134, vcc
	v_cmp_eq_u32_e32 vcc, v11, v94
	s_add_i32 s4, s4, 16
	v_cmp_eq_u32_e64 s[0:1], 0, v93
	v_cndmask_b32_e32 v11, 0, v134, vcc
	v_cmp_eq_u32_e32 vcc, v10, v94
	v_lshl_add_u32 v139, v94, 3, s4
	v_perm_b32 v82, v6, v3, s83
	v_cndmask_b32_e32 v10, 0, v134, vcc
	v_cmp_eq_u32_e32 vcc, v13, v94
	v_perm_b32 v81, v4, v1, s83
	v_perm_b32 v83, v7, v5, s83
	v_cndmask_b32_e32 v13, 0, v134, vcc
	v_cmp_eq_u32_e32 vcc, v12, v94
	v_perm_b32 v80, v2, v0, s83
	v_perm_b32 v85, v13, v10, s83
	v_cndmask_b32_e32 v12, 0, v134, vcc
	v_cmp_eq_u32_e32 vcc, v14, v94
	v_perm_b32 v84, v11, v9, s83
	s_nop 0
	v_cndmask_b32_e32 v14, 0, v134, vcc
	v_cmp_eq_u32_e32 vcc, v15, v94
	s_nop 1
	v_cndmask_b32_e32 v15, 0, v134, vcc
	v_cmp_eq_u32_e32 vcc, v16, v94
	v_perm_b32 v86, v15, v12, s83
	s_nop 0
	v_cndmask_b32_e32 v16, 0, v134, vcc
	v_cmp_lt_i32_e32 vcc, v17, v18
	v_perm_b32 v87, v16, v14, s83
	s_nop 0
	v_cndmask_b32_e32 v17, v132, v17, vcc
	v_lshlrev_b32_e32 v140, 2, v17
	v_lshlrev_b32_e32 v175, 2, v91
	global_load_dword v172, v175, s[42:43]
	global_load_dword v173, v175, s[36:37]
	global_load_dword v174, v175, s[40:41]
	s_setprio 1
	v_xad_u32 v148, v88, v8, v95
	ds_read_b128 v[0:3], v148 offset:16384
	ds_read_b128 v[4:7], v148 offset:49152
	s_waitcnt lgkmcnt(1)
	v_mfma_f32_32x32x16_bf16 v[32:47], v[48:51], v[0:3], 0
	v_or_b32_e32 v0, 32, v88
	v_xad_u32 v150, v0, v8, v95
	s_waitcnt lgkmcnt(0)
	v_mfma_f32_32x32x16_bf16 v[16:31], v[48:51], v[4:7], 0
	ds_read_b128 v[0:3], v150 offset:16384
	ds_read_b128 v[4:7], v150 offset:49152
	s_waitcnt lgkmcnt(1)
	v_mfma_f32_32x32x16_bf16 v[32:47], v[52:55], v[0:3], v[32:47]
	v_or_b32_e32 v0, 64, v88
	v_xad_u32 v145, v0, v8, v95
	s_waitcnt lgkmcnt(0)
	v_mfma_f32_32x32x16_bf16 v[16:31], v[52:55], v[4:7], v[16:31]
	ds_read_b128 v[0:3], v145 offset:16384
	ds_read_b128 v[4:7], v145 offset:49152
	s_waitcnt lgkmcnt(1)
	v_mfma_f32_32x32x16_bf16 v[32:47], v[56:59], v[0:3], v[32:47]
	v_or_b32_e32 v0, 0x60, v88
	v_xad_u32 v149, v0, v8, v95
	s_waitcnt lgkmcnt(0)
	v_mfma_f32_32x32x16_bf16 v[16:31], v[56:59], v[4:7], v[16:31]
	ds_read_b128 v[0:3], v149 offset:16384
	ds_read_b128 v[4:7], v149 offset:49152
	s_waitcnt lgkmcnt(1)
	v_mfma_f32_32x32x16_bf16 v[32:47], v[60:63], v[0:3], v[32:47]
	v_or_b32_e32 v0, 0x80, v88
	v_xad_u32 v144, v0, v8, v95
	s_waitcnt lgkmcnt(0)
	v_mfma_f32_32x32x16_bf16 v[16:31], v[60:63], v[4:7], v[16:31]
	ds_read_b128 v[0:3], v144 offset:16384
	ds_read_b128 v[4:7], v144 offset:49152
	s_waitcnt lgkmcnt(1)
	v_mfma_f32_32x32x16_bf16 v[32:47], v[64:67], v[0:3], v[32:47]
	v_or_b32_e32 v0, 0xa0, v88
	v_xad_u32 v147, v0, v8, v95
	s_waitcnt lgkmcnt(0)
	v_mfma_f32_32x32x16_bf16 v[16:31], v[64:67], v[4:7], v[16:31]
	ds_read_b128 v[0:3], v147 offset:16384
	ds_read_b128 v[4:7], v147 offset:49152
	s_waitcnt lgkmcnt(1)
	v_mfma_f32_32x32x16_bf16 v[32:47], v[68:71], v[0:3], v[32:47]
	v_or_b32_e32 v0, 0xc0, v88
	v_xad_u32 v143, v0, v8, v95
	s_waitcnt lgkmcnt(0)
	v_mfma_f32_32x32x16_bf16 v[16:31], v[68:71], v[4:7], v[16:31]
	ds_read_b128 v[0:3], v143 offset:16384
	ds_read_b128 v[4:7], v143 offset:49152
	s_waitcnt lgkmcnt(1)
	v_mfma_f32_32x32x16_bf16 v[32:47], v[72:75], v[0:3], v[32:47]
	v_or_b32_e32 v0, 0xe0, v88
	v_xad_u32 v146, v0, v8, v95
	s_waitcnt lgkmcnt(0)
	v_mfma_f32_32x32x16_bf16 v[16:31], v[72:75], v[4:7], v[16:31]
	ds_read_b128 v[0:3], v146 offset:16384
	ds_read_b128 v[4:7], v146 offset:49152
	s_waitcnt lgkmcnt(1)
	v_mfma_f32_32x32x16_bf16 v[32:47], v[76:79], v[0:3], v[32:47]
	s_waitcnt lgkmcnt(0)
	v_mfma_f32_32x32x16_bf16 v[16:31], v[76:79], v[4:7], v[16:31]
	v_mfma_f32_32x32x16_bf16 v[0:15], v[48:51], v[80:83], 0
	v_mfma_f32_32x32x16_bf16 v[0:15], v[52:55], v[84:87], v[0:15]
	s_setprio 0
	v_lshlrev_b32_e32 v88, 2, v91
	s_waitcnt vmcnt(0)
	ds_read_b32 v251, v167
	v_mul_f32_e32 v97, 0xbfb8aa3b, v173
	v_mul_f32_e32 v96, 0xbfb8aa3b, v174
	v_fmamk_f32 v32, v32, 0xbfb8aa3b, v97
	v_fmamk_f32 v34, v34, 0xbfb8aa3b, v97
	v_fmamk_f32 v33, v33, 0xbfb8aa3b, v97
	v_fmamk_f32 v35, v35, 0xbfb8aa3b, v97
	v_fmamk_f32 v16, v16, 0xbfb8aa3b, v96
	v_fmamk_f32 v17, v17, 0xbfb8aa3b, v96
	v_exp_f32_e32 v32, v32
	v_exp_f32_e32 v34, v34
	v_exp_f32_e32 v33, v33
	v_exp_f32_e32 v107, v35
	v_exp_f32_e32 v91, v16
	v_exp_f32_e32 v98, v17
	v_add_f32_e32 v32, 1.0, v32
	v_add_f32_e32 v108, 1.0, v34
	v_add_f32_e32 v33, 1.0, v33
	v_rcp_f32_e32 v109, v32
	v_rcp_f32_e32 v111, v33
	v_add_f32_e32 v91, 1.0, v91
	v_rcp_f32_e32 v110, v91
	v_add_f32_e32 v98, 1.0, v98
	v_rcp_f32_e32 v112, v98
	v_fmamk_f32 v18, v18, 0xbfb8aa3b, v96
	v_exp_f32_e32 v18, v18
	v_fmamk_f32 v20, v20, 0xbfb8aa3b, v96
	v_add_f32_e32 v18, 1.0, v18
	v_exp_f32_e32 v20, v20
	v_fmamk_f32 v19, v19, 0xbfb8aa3b, v96
	v_exp_f32_e32 v19, v19
	v_fmamk_f32 v21, v21, 0xbfb8aa3b, v96
	s_waitcnt lgkmcnt(0)
	v_mul_f32_e32 v33, 0x3fb8aa3b, v251
	v_mul_f32_e32 v16, v109, v33
	v_exp_f32_e32 v32, v16
	v_mul_f32_e32 v17, v111, v33
	v_exp_f32_e32 v34, v17
	v_rcp_f32_e32 v16, v108
	v_rcp_f32_e32 v17, v18
	v_fma_f32 v18, -v32, v32, 1.0
	v_sqrt_f32_e32 v18, v18
	v_mul_f32_e32 v16, v16, v33
	v_add_f32_e32 v19, 1.0, v19
	v_mul_f32_e32 v18, v110, v18
	v_mul_f32_e32 v18, v0, v18
	v_exp_f32_e32 v0, v16
	v_add_f32_e32 v16, 1.0, v107
	v_rcp_f32_e32 v16, v16
	v_rcp_f32_e32 v19, v19
	v_fma_f32 v91, -v0, v0, 1.0
	v_sqrt_f32_e32 v91, v91
	v_mul_f32_e32 v16, v16, v33
	v_exp_f32_e32 v98, v16
	v_fmamk_f32 v16, v36, 0xbfb8aa3b, v97
	v_exp_f32_e32 v16, v16
	v_mul_f32_e32 v91, v17, v91
	v_add_f32_e32 v17, 1.0, v20
	v_fma_f32 v36, -v98, v98, 1.0
	v_add_f32_e32 v16, 1.0, v16
	v_rcp_f32_e32 v16, v16
	v_sqrt_f32_e32 v36, v36
	v_rcp_f32_e32 v17, v17
	v_mul_f32_e32 v16, v16, v33
	v_exp_f32_e32 v20, v16
	v_fmamk_f32 v16, v37, 0xbfb8aa3b, v97
	v_exp_f32_e32 v16, v16
	v_mul_f32_e32 v36, v19, v36
	v_fma_f32 v19, -v20, v20, 1.0
	v_sqrt_f32_e32 v19, v19
	v_add_f32_e32 v16, 1.0, v16
	v_rcp_f32_e32 v16, v16
	v_exp_f32_e32 v21, v21
	v_mul_f32_e32 v17, v17, v19
	v_mul_f32_e32 v19, v4, v17
	v_mul_f32_e32 v16, v16, v33
	v_exp_f32_e32 v37, v16
	v_fmamk_f32 v16, v38, 0xbfb8aa3b, v97
	v_exp_f32_e32 v16, v16
	v_add_f32_e32 v4, 1.0, v21
	v_fmamk_f32 v21, v22, 0xbfb8aa3b, v96
	v_add_f32_e32 v16, 1.0, v16
	v_rcp_f32_e32 v16, v16
	v_fma_f32 v17, -v37, v37, 1.0
	v_exp_f32_e32 v21, v21
	v_rcp_f32_e32 v4, v4
	v_mul_f32_e32 v16, v16, v33
	v_sqrt_f32_e32 v17, v17
	v_exp_f32_e32 v38, v16
	v_add_f32_e32 v16, 1.0, v21
	v_fmamk_f32 v21, v39, 0xbfb8aa3b, v97
	v_mul_f32_e32 v4, v4, v17
	v_fma_f32 v17, -v38, v38, 1.0
	v_rcp_f32_e32 v16, v16
	v_sqrt_f32_e32 v17, v17
	v_exp_f32_e32 v21, v21
	v_fmamk_f32 v22, v23, 0xbfb8aa3b, v96
	v_mul_f32_e32 v23, v16, v17
	v_add_f32_e32 v16, 1.0, v21
	v_rcp_f32_e32 v16, v16
	v_fmamk_f32 v21, v40, 0xbfb8aa3b, v97
	v_exp_f32_e32 v21, v21
	v_mul_f32_e32 v16, v16, v33
	v_exp_f32_e32 v39, v16
	v_add_f32_e32 v16, 1.0, v21
	v_rcp_f32_e32 v16, v16
	v_exp_f32_e32 v22, v22
	v_fmamk_f32 v21, v24, 0xbfb8aa3b, v96
	v_mul_f32_e32 v16, v16, v33
	v_add_f32_e32 v17, 1.0, v22
	v_fma_f32 v22, -v39, v39, 1.0
	v_sqrt_f32_e32 v24, v22
	v_exp_f32_e32 v22, v16
	v_fmamk_f32 v16, v41, 0xbfb8aa3b, v97
	v_exp_f32_e32 v16, v16
	v_exp_f32_e32 v21, v21
	v_fma_f32 v40, -v22, v22, 1.0
	v_rcp_f32_e32 v17, v17
	v_add_f32_e32 v16, 1.0, v16
	v_rcp_f32_e32 v16, v16
	v_add_f32_e32 v21, 1.0, v21
	v_rcp_f32_e32 v21, v21
	v_sqrt_f32_e32 v40, v40
	v_mul_f32_e32 v16, v16, v33
	v_mul_f32_e32 v24, v17, v24
	v_mul_f32_e32 v17, v21, v40
	v_exp_f32_e32 v40, v16
	v_fmamk_f32 v16, v42, 0xbfb8aa3b, v97
	v_fmamk_f32 v25, v25, 0xbfb8aa3b, v96
	v_exp_f32_e32 v16, v16
	v_exp_f32_e32 v25, v25
	v_fma_f32 v35, -v34, v34, 1.0
	v_sqrt_f32_e32 v35, v35
	v_add_f32_e32 v16, 1.0, v16
	v_add_f32_e32 v21, 1.0, v25
	v_rcp_f32_e32 v16, v16
	v_rcp_f32_e32 v25, v21
	v_fma_f32 v21, -v40, v40, 1.0
	v_sqrt_f32_e32 v41, v21
	v_fmamk_f32 v21, v26, 0xbfb8aa3b, v96
	v_mul_f32_e32 v16, v16, v33
	v_exp_f32_e32 v26, v21
	v_mul_f32_e32 v21, v8, v17
	v_mul_f32_e32 v8, v25, v41
	v_exp_f32_e32 v41, v16
	v_fmamk_f32 v16, v43, 0xbfb8aa3b, v97
	v_exp_f32_e32 v16, v16
	v_add_f32_e32 v17, 1.0, v26
	v_fma_f32 v25, -v41, v41, 1.0
	v_fmamk_f32 v26, v27, 0xbfb8aa3b, v96
	v_add_f32_e32 v16, 1.0, v16
	v_rcp_f32_e32 v16, v16
	v_rcp_f32_e32 v17, v17
	v_sqrt_f32_e32 v25, v25
	v_mul_f32_e32 v16, v16, v33
	v_exp_f32_e32 v26, v26
	v_exp_f32_e32 v99, v16
	v_mul_f32_e32 v100, v17, v25
	v_fmamk_f32 v25, v44, 0xbfb8aa3b, v97
	v_add_f32_e32 v16, 1.0, v26
	v_fmamk_f32 v26, v28, 0xbfb8aa3b, v96
	v_fma_f32 v17, -v99, v99, 1.0
	v_exp_f32_e32 v25, v25
	v_rcp_f32_e32 v16, v16
	v_sqrt_f32_e32 v17, v17
	v_exp_f32_e32 v26, v26
	v_add_f32_e32 v25, 1.0, v25
	v_rcp_f32_e32 v25, v25
	v_mul_f32_e32 v101, v16, v17
	v_add_f32_e32 v16, 1.0, v26
	v_fmamk_f32 v26, v29, 0xbfb8aa3b, v96
	v_exp_f32_e32 v26, v26
	v_rcp_f32_e32 v17, v16
	v_mul_f32_e32 v16, v25, v33
	v_fmamk_f32 v25, v45, 0xbfb8aa3b, v97
	v_exp_f32_e32 v25, v25
	v_add_f32_e32 v26, 1.0, v26
	v_rcp_f32_e32 v42, v26
	v_fmamk_f32 v26, v46, 0xbfb8aa3b, v97
	v_exp_f32_e32 v26, v26
	v_add_f32_e32 v25, 1.0, v25
	v_rcp_f32_e32 v25, v25
	v_fmamk_f32 v27, v30, 0xbfb8aa3b, v96
	v_exp_f32_e32 v27, v27
	v_add_f32_e32 v26, 1.0, v26
	v_rcp_f32_e32 v26, v26
	v_mul_f32_e32 v25, v25, v33
	v_exp_f32_e32 v43, v25
	v_add_f32_e32 v25, 1.0, v27
	v_rcp_f32_e32 v44, v25
	v_mul_f32_e32 v25, v26, v33
	v_fmamk_f32 v26, v47, 0xbfb8aa3b, v97
	v_exp_f32_e32 v26, v26
	v_fmamk_f32 v27, v31, 0xbfb8aa3b, v96
	v_exp_f32_e32 v27, v27
	v_add_f32_e32 v26, 1.0, v26
	v_rcp_f32_e32 v26, v26
	v_exp_f32_e32 v16, v16
	v_fmac_f32_e32 v18, 0, v32
	v_mul_f32_e32 v35, v112, v35
	v_exp_f32_e32 v45, v25
	v_add_f32_e32 v25, 1.0, v27
	v_mul_f32_e32 v31, v34, v18
	v_rcp_f32_e32 v46, v25
	v_mul_f32_e32 v25, v26, v33
	v_fmac_f32_e32 v31, v1, v35
	v_mul_f32_e32 v33, v32, v34
	v_mul_f32_e32 v30, v0, v31
	v_mul_f32_e32 v34, v0, v33
	v_fma_f32 v0, -v16, v16, 1.0
	v_sqrt_f32_e32 v1, v0
	v_fmac_f32_e32 v30, v2, v91
	v_fmac_f32_e32 v21, 0, v22
	v_fma_f32 v2, -v43, v43, 1.0
	v_exp_f32_e32 v47, v25
	v_mul_f32_e32 v25, v40, v21
	v_mov_b32_e32 v0, v89
	v_sqrt_f32_e32 v2, v2
	v_fmac_f32_e32 v25, v9, v8
	v_pk_mul_f32 v[8:9], v[16:17], v[0:1]
	v_mul_f32_e32 v29, v98, v30
	v_fmac_f32_e32 v19, 0, v20
	v_fmac_f32_e32 v8, v12, v9
	v_fmac_f32_e32 v29, v3, v36
	v_mul_f32_e32 v28, v37, v19
	v_mov_b32_e32 v3, v8
	v_fmac_f32_e32 v28, v5, v4
	v_pk_mul_f32 v[4:5], v[42:43], v[2:3]
	v_fma_f32 v0, -v45, v45, 1.0
	v_fmac_f32_e32 v5, v13, v4
	v_sqrt_f32_e32 v4, v0
	v_mul_f32_e32 v27, v38, v28
	v_fmac_f32_e32 v27, v6, v23
	v_mul_f32_e32 v26, v39, v27
	v_fmac_f32_e32 v26, v7, v24
	v_pk_mul_f32 v[6:7], v[44:45], v[4:5]
	v_fma_f32 v0, -v47, v47, 1.0
	v_fmac_f32_e32 v7, v14, v6
	v_sqrt_f32_e32 v6, v0
	ds_bpermute_b32 v0, v140, v29
	v_mul_f32_e32 v24, v41, v25
	v_mul_f32_e32 v35, v98, v34
	v_mul_f32_e32 v36, v20, v37
	v_fmac_f32_e32 v24, v10, v100
	v_mul_f32_e32 v37, v38, v36
	v_mul_f32_e32 v23, v99, v24
	ds_bpermute_b32 v13, v140, v35
	v_mul_f32_e32 v38, v39, v37
	v_fmac_f32_e32 v23, v11, v101
	v_pk_mul_f32 v[10:11], v[46:47], v[6:7]
	s_waitcnt lgkmcnt(1)
	v_cndmask_b32_e64 v14, v29, v0, s[0:1]
	v_fmac_f32_e32 v11, v15, v10
	v_cndmask_b32_e64 v10, v0, v29, s[0:1]
	ds_bpermute_b32 v0, v140, v38
	ds_bpermute_b32 v3, v140, v26
	v_mul_f32_e32 v39, v22, v40
	v_mul_f32_e32 v40, v41, v39
	s_waitcnt lgkmcnt(2)
	v_cndmask_b32_e64 v1, v13, v35, s[0:1]
	v_mul_f32_e32 v12, v99, v40
	v_mul_f32_e32 v9, v16, v43
	v_cndmask_b32_e64 v2, v35, v13, s[0:1]
	v_fmac_f32_e32 v10, 0, v1
	v_mul_f32_e32 v4, v45, v9
	v_mul_f32_e32 v15, v35, v13
	v_fmac_f32_e32 v14, v2, v10
	s_waitcnt lgkmcnt(1)
	v_cndmask_b32_e64 v1, v0, v38, s[0:1]
	s_waitcnt lgkmcnt(0)
	v_cndmask_b32_e64 v17, v3, v26, s[0:1]
	v_cndmask_b32_e64 v41, v26, v3, s[0:1]
	ds_bpermute_b32 v2, v140, v12
	ds_bpermute_b32 v3, v140, v23
	v_mul_f32_e32 v6, v47, v4
	v_cndmask_b32_e64 v0, v38, v0, s[0:1]
	v_mul_f32_e32 v42, v15, v1
	v_fmac_f32_e32 v17, v1, v14
	v_mul_f32_e32 v43, v0, v42
	v_fmac_f32_e32 v41, v0, v17
	ds_bpermute_b32 v1, v140, v6
	ds_bpermute_b32 v0, v140, v11
	s_waitcnt lgkmcnt(3)
	v_cndmask_b32_e64 v47, v2, v12, s[0:1]
	s_waitcnt lgkmcnt(2)
	v_cndmask_b32_e64 v44, v3, v23, s[0:1]
	v_cndmask_b32_e64 v2, v12, v2, s[0:1]
	v_cndmask_b32_e64 v45, v23, v3, s[0:1]
	v_mul_f32_e32 v46, v47, v43
	v_fmac_f32_e32 v44, v47, v41
	v_mul_f32_e32 v47, v2, v46
	v_fmac_f32_e32 v45, v2, v44
	s_waitcnt lgkmcnt(1)
	v_cndmask_b32_e64 v2, v1, v6, s[0:1]
	s_waitcnt lgkmcnt(0)
	v_cndmask_b32_e64 v91, v0, v11, s[0:1]
	v_mul_f32_e32 v96, v2, v47
	v_fmac_f32_e32 v91, v2, v45
	s_and_saveexec_b64 s[4:5], s[0:1]
	v_mul_f32_e32 v3, v91, v1
	v_mul_f32_e32 v2, v96, v1
	v_add_f32_e32 v3, v3, v0
	ds_write_b64 v139, v[2:3]
	s_or_b64 exec, exec, s[4:5]
	s_cmp_gt_i32 s62, 0
	s_cselect_b64 s[12:13], -1, 0
	s_cmp_lt_i32 s62, 1
	v_mul_i32_i24_e32 v141, 0xffffff08, v94
	s_waitcnt lgkmcnt(0)
	s_barrier
	s_cbranch_scc1 .LBB0_327
	s_cmp_lt_u32 s62, 8
	s_cbranch_scc1 .LBB0_328
	v_add_u32_e32 v95, v95, v141
	s_and_b32 s4, s62, 0x7ffffff8
	v_mov_b32_e32 v0, 1.0
	v_mov_b32_e32 v3, 0
	s_mov_b32 s5, 0
